# phase 11 recurrences with block-level LDS staging of f32 k/q/alpha/v operands
# speedup vs baseline: 1.1130x; 1.0604x over previous
.LBB0_34:
	s_andn2_b64 vcc, exec, s[0:1]
	s_cbranch_vccnz .LBB0_96
	s_lshl_b32 s0, s58, 2
	s_bfe_u32 s1, s26, 0x20006
	s_or_b32 s18, s1, s0
	s_lshl_b32 s19, s59, 2
	s_cmpk_lt_i32 s18, 0x400
	s_cselect_b64 s[2:3], -1, 0
	v_readlane_b32 s0, v255, 15
	v_cndmask_b32_e64 v0, 0, 1, s[2:3]
	s_cmp_lt_i32 s0, 4
	s_mov_b64 s[0:1], -1
	v_cmp_ne_u32_e64 s[6:7], 1, v0
	s_cbranch_scc1 .LBB0_58
	s_and_b64 vcc, exec, s[6:7]
	s_mov_b64 s[24:25], 0x18000
	s_cbranch_vccnz .LBB0_57
	v_readlane_b32 s0, v255, 18
	v_readlane_b32 s1, v255, 19
	s_load_dwordx2 s[8:9], s[0:1], 0xf0
	v_readlane_b32 s5, v255, 15
	v_and_b32_e32 v46, 15, v198
	v_lshrrev_b32_e32 v5, 4, v198
	v_lshlrev_b32_e32 v2, 4, v46
	v_lshlrev_b32_e32 v4, 13, v46
	s_mov_b32 s17, 0xffff0000
	s_mov_b32 s23, s18
	v_and_b32_e32 v42, 3, v198
	v_lshrrev_b32_e32 v44, 2, v198
	v_lshlrev_b32_e32 v29, 8, v42
	v_lshl_add_u32 v29, v44, 4, v29
	s_lshl_b32 s0, s5, 10
	v_add_u32_e32 v29, s0, v29
	v_lshrrev_b32_e32 v30, 1, v42
	v_lshlrev_b32_e32 v30, 8, v30
	v_lshl_add_u32 v30, v44, 4, v30
	v_and_b32_e32 v42, 1, v198
	v_lshl_add_u32 v30, v42, 3, v30
	s_lshl_b32 s0, s5, 9
	s_add_u32 s0, s0, 16384
	v_add_u32_e32 v30, s0, v30
	v_min_u32_e32 v42, 31, v198
	v_lshlrev_b32_e32 v31, 3, v42
	s_lshl_b32 s0, s5, 8
	s_add_u32 s0, s0, 20480
	v_add_u32_e32 v31, s0, v31
	v_lshlrev_b32_e32 v35, 3, v198
	s_waitcnt lgkmcnt(0)
.Lret2_item:
	s_lshr_b32 s0, s23, 5
	s_and_b32 s1, s23, 31
	s_lshr_b32 s2, s0, 2
	s_and_b32 s3, s0, 3
	s_lshl_b32 s4, s1, 4
	v_lshl_add_u32 v46, v5, 2, s4
	s_and_b32 s4, s1, 3
	s_lshl_b32 s4, s4, 5
	s_add_u32 s4, s4, 128
	v_lshl_add_u32 v3, v5, 3, s4
	s_lshl_b32 s4, s3, 8
	s_add_u32 s4, s4, 1024
	v_lshl_add_u32 v32, v198, 2, s4
	s_add_u32 s4, s4, 4096
	v_lshl_add_u32 v33, v198, 2, s4
	s_lshl_b32 s4, s3, 9
	s_and_b32 s5, s1, 28
	s_lshl_b32 s5, s5, 4
	s_add_u32 s4, s4, s5
	s_add_u32 s4, s4, 2048
	v_min_u32_e32 v42, 31, v198
	v_lshl_add_u32 v34, v42, 2, s4
	v_cmp_lt_u32_e32 vcc, 15, v198
	v_add_u32_e32 v44, 4032, v34
	s_nop 1
	v_cndmask_b32_e32 v34, v34, v44, vcc
	v_readlane_b32 s5, v255, 15
	s_mul_i32 s4, s2, 0x1800000
	s_mul_i32 s1, s5, 0x3000
	s_add_u32 s4, s4, s1
	s_add_u32 s4, s4, 0x3bc0400
	s_add_u32 s10, s8, s4
	s_addc_u32 s11, s9, 0
	s_lshl_b32 s4, s2, 22
	s_lshl_b32 s1, s5, 11
	s_add_u32 s4, s4, s1
	s_lshl_b32 s1, s3, 9
	s_add_u32 s4, s4, s1
	s_add_u32 s4, s4, 0xfd40400
	s_add_u32 s12, s8, s4
	s_addc_u32 s13, s9, 0
	s_lshl_b32 s4, s2, 23
	s_add_u32 s4, s4, s1
	s_add_u32 s4, s4, 333188096
	s_add_u32 s14, s8, s4
	s_addc_u32 s15, s9, 0
	s_lshr_b32 s4, 0x80000, s3
	s_sub_u32 s4, 0x3f800000, s4
	v_mov_b32_e32 v40, s4
	s_movk_i32 s20, 256
	s_movk_i32 s21, 24832
	s_mov_b32 s22, 49408
	v_add_u32_e32 v26, s20, v29
	v_add_u32_e32 v27, s20, v30
	v_add_u32_e32 v28, s20, v31
	global_load_dword v84, v32, s[10:11]
	global_load_dword v85, v32, s[10:11] offset:-1024
	global_load_dword v86, v33, s[10:11]
	global_load_dword v87, v33, s[10:11] offset:-1024
	global_load_dword v88, v34, s[10:11]
	global_load_dword v90, v35, s[12:13]
	global_load_dword v91, v35, s[12:13] offset:4
	s_add_u32 s10, s10, 0x18000
	s_addc_u32 s11, s11, 0
	s_add_u32 s12, s12, 0x4000
	s_addc_u32 s13, s13, 0
	s_waitcnt vmcnt(0)
	v_lshlrev_b32_e32 v108, 16, v84
	v_lshlrev_b32_e32 v109, 16, v85
	v_and_b32_e32 v110, s17, v84
	v_and_b32_e32 v111, s17, v85
	v_lshlrev_b32_e32 v112, 16, v86
	v_lshlrev_b32_e32 v113, 16, v87
	v_and_b32_e32 v114, s17, v86
	v_and_b32_e32 v115, s17, v87
	v_lshlrev_b32_e32 v116, 16, v88
	v_and_b32_e32 v117, s17, v88
	ds_write_b128 v26, v[108:111] offset:0
	ds_write_b128 v26, v[112:115] offset:8192
	ds_write_b64 v27, v[90:91]
	ds_write_b64 v28, v[116:117]
	v_add_u32_e32 v26, s21, v29
	v_add_u32_e32 v27, s21, v30
	v_add_u32_e32 v28, s21, v31
	global_load_dword v84, v32, s[10:11]
	global_load_dword v85, v32, s[10:11] offset:-1024
	global_load_dword v86, v33, s[10:11]
	global_load_dword v87, v33, s[10:11] offset:-1024
	global_load_dword v88, v34, s[10:11]
	global_load_dword v90, v35, s[12:13]
	global_load_dword v91, v35, s[12:13] offset:4
	s_add_u32 s10, s10, 0x18000
	s_addc_u32 s11, s11, 0
	s_add_u32 s12, s12, 0x4000
	s_addc_u32 s13, s13, 0
	s_waitcnt vmcnt(0)
	v_lshlrev_b32_e32 v108, 16, v84
	v_lshlrev_b32_e32 v109, 16, v85
	v_and_b32_e32 v110, s17, v84
	v_and_b32_e32 v111, s17, v85
	v_lshlrev_b32_e32 v112, 16, v86
	v_lshlrev_b32_e32 v113, 16, v87
	v_and_b32_e32 v114, s17, v86
	v_and_b32_e32 v115, s17, v87
	v_lshlrev_b32_e32 v116, 16, v88
	v_and_b32_e32 v117, s17, v88
	ds_write_b128 v26, v[108:111] offset:0
	ds_write_b128 v26, v[112:115] offset:8192
	ds_write_b64 v27, v[90:91]
	ds_write_b64 v28, v[116:117]
	v_add_u32_e32 v26, s22, v29
	v_add_u32_e32 v27, s22, v30
	v_add_u32_e32 v28, s22, v31
	v_add_u32_e32 v22, s20, v2
	v_add_u32_e32 v23, s20, v3
	v_add_u32_e32 v24, s21, v2
	v_add_u32_e32 v25, s21, v3
	v_mov_b32_e32 v6, 0
	v_mov_b32_e32 v7, 0
	v_mov_b32_e32 v8, 0
	v_mov_b32_e32 v9, 0
	v_mov_b32_e32 v10, 0
	v_mov_b32_e32 v11, 0
	v_mov_b32_e32 v12, 0
	v_mov_b32_e32 v13, 0
	v_mov_b32_e32 v14, 0
	v_mov_b32_e32 v15, 0
	v_mov_b32_e32 v16, 0
	v_mov_b32_e32 v17, 0
	v_mov_b32_e32 v18, 0
	v_mov_b32_e32 v19, 0
	v_mov_b32_e32 v20, 0
	v_mov_b32_e32 v21, 0
	s_mov_b32 s16, 0
	s_mov_b32 s2, 0x10001
	s_mov_b32 s3, 0x10001
	s_waitcnt vmcnt(0) lgkmcnt(0)
	s_barrier
	ds_read_b128 v[48:51], v22 offset:8192
	ds_read_b128 v[52:55], v22 offset:8448
	ds_read_b128 v[56:59], v22 offset:8704
	ds_read_b128 v[60:63], v22 offset:8960
	ds_read_b64 v[64:65], v23 offset:20480
.Lret2_loop:
	global_load_dword v84, v32, s[10:11]
	global_load_dword v85, v32, s[10:11] offset:-1024
	global_load_dword v86, v33, s[10:11]
	global_load_dword v87, v33, s[10:11] offset:-1024
	global_load_dword v88, v34, s[10:11]
	global_load_dword v90, v35, s[12:13]
	global_load_dword v91, v35, s[12:13] offset:4
	s_add_u32 s10, s10, 0x18000
	s_addc_u32 s11, s11, 0
	s_add_u32 s12, s12, 0x4000
	s_addc_u32 s13, s13, 0
	ds_read_b128 v[66:69], v22 offset:9216
	ds_read_b128 v[70:73], v22 offset:9472
	ds_read_b128 v[74:77], v22 offset:9728
	ds_read_b128 v[78:81], v22 offset:9984
	ds_read_b64 v[82:83], v23 offset:20736
	s_waitcnt lgkmcnt(5)
	v_pk_mul_f32 v[42:43], v[64:65], v[48:49] op_sel_hi:[1,0]
	v_pk_fma_f32 v[6:7], v[6:7], v[40:41], v[42:43] op_sel_hi:[1,0,1]
	v_pk_mul_f32 v[38:39], v[6:7], v[48:49] op_sel:[0,1] op_sel_hi:[1,1]
	v_pk_mul_f32 v[44:45], v[64:65], v[50:51] op_sel_hi:[1,0]
	v_pk_fma_f32 v[8:9], v[8:9], v[40:41], v[44:45] op_sel_hi:[1,0,1]
	v_pk_fma_f32 v[38:39], v[8:9], v[50:51], v[38:39] op_sel:[0,1,0] op_sel_hi:[1,1,1]
	v_pk_mul_f32 v[42:43], v[64:65], v[52:53] op_sel_hi:[1,0]
	v_pk_fma_f32 v[10:11], v[10:11], v[40:41], v[42:43] op_sel_hi:[1,0,1]
	v_pk_fma_f32 v[38:39], v[10:11], v[52:53], v[38:39] op_sel:[0,1,0] op_sel_hi:[1,1,1]
	v_pk_mul_f32 v[44:45], v[64:65], v[54:55] op_sel_hi:[1,0]
	v_pk_fma_f32 v[12:13], v[12:13], v[40:41], v[44:45] op_sel_hi:[1,0,1]
	v_pk_fma_f32 v[38:39], v[12:13], v[54:55], v[38:39] op_sel:[0,1,0] op_sel_hi:[1,1,1]
	v_pk_mul_f32 v[42:43], v[64:65], v[56:57] op_sel_hi:[1,0]
	v_pk_fma_f32 v[14:15], v[14:15], v[40:41], v[42:43] op_sel_hi:[1,0,1]
	v_pk_fma_f32 v[38:39], v[14:15], v[56:57], v[38:39] op_sel:[0,1,0] op_sel_hi:[1,1,1]
	v_pk_mul_f32 v[44:45], v[64:65], v[58:59] op_sel_hi:[1,0]
	v_pk_fma_f32 v[16:17], v[16:17], v[40:41], v[44:45] op_sel_hi:[1,0,1]
	v_pk_fma_f32 v[38:39], v[16:17], v[58:59], v[38:39] op_sel:[0,1,0] op_sel_hi:[1,1,1]
	v_pk_mul_f32 v[42:43], v[64:65], v[60:61] op_sel_hi:[1,0]
	v_pk_fma_f32 v[18:19], v[18:19], v[40:41], v[42:43] op_sel_hi:[1,0,1]
	v_pk_fma_f32 v[38:39], v[18:19], v[60:61], v[38:39] op_sel:[0,1,0] op_sel_hi:[1,1,1]
	v_pk_mul_f32 v[44:45], v[64:65], v[62:63] op_sel_hi:[1,0]
	v_pk_fma_f32 v[20:21], v[20:21], v[40:41], v[44:45] op_sel_hi:[1,0,1]
	v_pk_fma_f32 v[38:39], v[20:21], v[62:63], v[38:39] op_sel:[0,1,0] op_sel_hi:[1,1,1]
	s_add_u32 s14, s14, 0x1000
	s_addc_u32 s15, s15, 0
	v_add_f32_dpp v38, v38, v38 quad_perm:[1,0,3,2] row_mask:0xf bank_mask:0xf bound_ctrl:1
	v_add_f32_dpp v39, v39, v39 quad_perm:[1,0,3,2] row_mask:0xf bank_mask:0xf bound_ctrl:1
	s_nop 0
	v_add_f32_dpp v38, v38, v38 quad_perm:[2,3,0,1] row_mask:0xf bank_mask:0xf bound_ctrl:1
	v_add_f32_dpp v39, v39, v39 quad_perm:[2,3,0,1] row_mask:0xf bank_mask:0xf bound_ctrl:1
	s_nop 0
	v_add_f32_dpp v38, v38, v38 row_half_mirror row_mask:0xf bank_mask:0xf bound_ctrl:1
	v_add_f32_dpp v39, v39, v39 row_half_mirror row_mask:0xf bank_mask:0xf bound_ctrl:1
	s_nop 0
	v_add_f32_dpp v38, v38, v38 row_mirror row_mask:0xf bank_mask:0xf bound_ctrl:1
	v_add_f32_dpp v39, v39, v39 row_mirror row_mask:0xf bank_mask:0xf bound_ctrl:1
	v_cvt_pk_bf16_f32 v47, v38, v39
	s_mov_b64 exec, s[2:3]
	global_store_dword v46, v47, s[14:15] offset:-4096
	s_mov_b64 exec, -1
	ds_read_b128 v[48:51], v22 offset:10240
	ds_read_b128 v[52:55], v22 offset:10496
	ds_read_b128 v[56:59], v22 offset:10752
	ds_read_b128 v[60:63], v22 offset:11008
	ds_read_b64 v[64:65], v23 offset:20992
	s_waitcnt lgkmcnt(5)
	v_pk_mul_f32 v[42:43], v[82:83], v[66:67] op_sel_hi:[1,0]
	v_pk_fma_f32 v[6:7], v[6:7], v[40:41], v[42:43] op_sel_hi:[1,0,1]
	v_pk_mul_f32 v[38:39], v[6:7], v[66:67] op_sel:[0,1] op_sel_hi:[1,1]
	v_pk_mul_f32 v[44:45], v[82:83], v[68:69] op_sel_hi:[1,0]
	v_pk_fma_f32 v[8:9], v[8:9], v[40:41], v[44:45] op_sel_hi:[1,0,1]
	v_pk_fma_f32 v[38:39], v[8:9], v[68:69], v[38:39] op_sel:[0,1,0] op_sel_hi:[1,1,1]
	v_pk_mul_f32 v[42:43], v[82:83], v[70:71] op_sel_hi:[1,0]
	v_pk_fma_f32 v[10:11], v[10:11], v[40:41], v[42:43] op_sel_hi:[1,0,1]
	v_pk_fma_f32 v[38:39], v[10:11], v[70:71], v[38:39] op_sel:[0,1,0] op_sel_hi:[1,1,1]
	v_pk_mul_f32 v[44:45], v[82:83], v[72:73] op_sel_hi:[1,0]
	v_pk_fma_f32 v[12:13], v[12:13], v[40:41], v[44:45] op_sel_hi:[1,0,1]
	v_pk_fma_f32 v[38:39], v[12:13], v[72:73], v[38:39] op_sel:[0,1,0] op_sel_hi:[1,1,1]
	v_pk_mul_f32 v[42:43], v[82:83], v[74:75] op_sel_hi:[1,0]
	v_pk_fma_f32 v[14:15], v[14:15], v[40:41], v[42:43] op_sel_hi:[1,0,1]
	v_pk_fma_f32 v[38:39], v[14:15], v[74:75], v[38:39] op_sel:[0,1,0] op_sel_hi:[1,1,1]
	v_pk_mul_f32 v[44:45], v[82:83], v[76:77] op_sel_hi:[1,0]
	v_pk_fma_f32 v[16:17], v[16:17], v[40:41], v[44:45] op_sel_hi:[1,0,1]
	v_pk_fma_f32 v[38:39], v[16:17], v[76:77], v[38:39] op_sel:[0,1,0] op_sel_hi:[1,1,1]
	v_pk_mul_f32 v[42:43], v[82:83], v[78:79] op_sel_hi:[1,0]
	v_pk_fma_f32 v[18:19], v[18:19], v[40:41], v[42:43] op_sel_hi:[1,0,1]
	v_pk_fma_f32 v[38:39], v[18:19], v[78:79], v[38:39] op_sel:[0,1,0] op_sel_hi:[1,1,1]
	v_pk_mul_f32 v[44:45], v[82:83], v[80:81] op_sel_hi:[1,0]
	v_pk_fma_f32 v[20:21], v[20:21], v[40:41], v[44:45] op_sel_hi:[1,0,1]
	v_pk_fma_f32 v[38:39], v[20:21], v[80:81], v[38:39] op_sel:[0,1,0] op_sel_hi:[1,1,1]
	s_add_u32 s14, s14, 0x1000
	s_addc_u32 s15, s15, 0
	v_add_f32_dpp v38, v38, v38 quad_perm:[1,0,3,2] row_mask:0xf bank_mask:0xf bound_ctrl:1
	v_add_f32_dpp v39, v39, v39 quad_perm:[1,0,3,2] row_mask:0xf bank_mask:0xf bound_ctrl:1
	s_nop 0
	v_add_f32_dpp v38, v38, v38 quad_perm:[2,3,0,1] row_mask:0xf bank_mask:0xf bound_ctrl:1
	v_add_f32_dpp v39, v39, v39 quad_perm:[2,3,0,1] row_mask:0xf bank_mask:0xf bound_ctrl:1
	s_nop 0
	v_add_f32_dpp v38, v38, v38 row_half_mirror row_mask:0xf bank_mask:0xf bound_ctrl:1
	v_add_f32_dpp v39, v39, v39 row_half_mirror row_mask:0xf bank_mask:0xf bound_ctrl:1
	s_nop 0
	v_add_f32_dpp v38, v38, v38 row_mirror row_mask:0xf bank_mask:0xf bound_ctrl:1
	v_add_f32_dpp v39, v39, v39 row_mirror row_mask:0xf bank_mask:0xf bound_ctrl:1
	v_cvt_pk_bf16_f32 v47, v38, v39
	s_mov_b64 exec, s[2:3]
	global_store_dword v46, v47, s[14:15] offset:-4096
	s_mov_b64 exec, -1
	ds_read_b128 v[66:69], v22 offset:11264
	ds_read_b128 v[70:73], v22 offset:11520
	ds_read_b128 v[74:77], v22 offset:11776
	ds_read_b128 v[78:81], v22 offset:12032
	ds_read_b64 v[82:83], v23 offset:21248
	s_waitcnt lgkmcnt(5)
	v_pk_mul_f32 v[42:43], v[64:65], v[48:49] op_sel_hi:[1,0]
	v_pk_fma_f32 v[6:7], v[6:7], v[40:41], v[42:43] op_sel_hi:[1,0,1]
	v_pk_mul_f32 v[38:39], v[6:7], v[48:49] op_sel:[0,1] op_sel_hi:[1,1]
	v_pk_mul_f32 v[44:45], v[64:65], v[50:51] op_sel_hi:[1,0]
	v_pk_fma_f32 v[8:9], v[8:9], v[40:41], v[44:45] op_sel_hi:[1,0,1]
	v_pk_fma_f32 v[38:39], v[8:9], v[50:51], v[38:39] op_sel:[0,1,0] op_sel_hi:[1,1,1]
	v_pk_mul_f32 v[42:43], v[64:65], v[52:53] op_sel_hi:[1,0]
	v_pk_fma_f32 v[10:11], v[10:11], v[40:41], v[42:43] op_sel_hi:[1,0,1]
	v_pk_fma_f32 v[38:39], v[10:11], v[52:53], v[38:39] op_sel:[0,1,0] op_sel_hi:[1,1,1]
	v_pk_mul_f32 v[44:45], v[64:65], v[54:55] op_sel_hi:[1,0]
	v_pk_fma_f32 v[12:13], v[12:13], v[40:41], v[44:45] op_sel_hi:[1,0,1]
	v_pk_fma_f32 v[38:39], v[12:13], v[54:55], v[38:39] op_sel:[0,1,0] op_sel_hi:[1,1,1]
	v_pk_mul_f32 v[42:43], v[64:65], v[56:57] op_sel_hi:[1,0]
	v_pk_fma_f32 v[14:15], v[14:15], v[40:41], v[42:43] op_sel_hi:[1,0,1]
	v_pk_fma_f32 v[38:39], v[14:15], v[56:57], v[38:39] op_sel:[0,1,0] op_sel_hi:[1,1,1]
	v_pk_mul_f32 v[44:45], v[64:65], v[58:59] op_sel_hi:[1,0]
	v_pk_fma_f32 v[16:17], v[16:17], v[40:41], v[44:45] op_sel_hi:[1,0,1]
	v_pk_fma_f32 v[38:39], v[16:17], v[58:59], v[38:39] op_sel:[0,1,0] op_sel_hi:[1,1,1]
	v_pk_mul_f32 v[42:43], v[64:65], v[60:61] op_sel_hi:[1,0]
	v_pk_fma_f32 v[18:19], v[18:19], v[40:41], v[42:43] op_sel_hi:[1,0,1]
	v_pk_fma_f32 v[38:39], v[18:19], v[60:61], v[38:39] op_sel:[0,1,0] op_sel_hi:[1,1,1]
	v_pk_mul_f32 v[44:45], v[64:65], v[62:63] op_sel_hi:[1,0]
	v_pk_fma_f32 v[20:21], v[20:21], v[40:41], v[44:45] op_sel_hi:[1,0,1]
	v_pk_fma_f32 v[38:39], v[20:21], v[62:63], v[38:39] op_sel:[0,1,0] op_sel_hi:[1,1,1]
	s_add_u32 s14, s14, 0x1000
	s_addc_u32 s15, s15, 0
	v_add_f32_dpp v38, v38, v38 quad_perm:[1,0,3,2] row_mask:0xf bank_mask:0xf bound_ctrl:1
	v_add_f32_dpp v39, v39, v39 quad_perm:[1,0,3,2] row_mask:0xf bank_mask:0xf bound_ctrl:1
	s_nop 0
	v_add_f32_dpp v38, v38, v38 quad_perm:[2,3,0,1] row_mask:0xf bank_mask:0xf bound_ctrl:1
	v_add_f32_dpp v39, v39, v39 quad_perm:[2,3,0,1] row_mask:0xf bank_mask:0xf bound_ctrl:1
	s_nop 0
	v_add_f32_dpp v38, v38, v38 row_half_mirror row_mask:0xf bank_mask:0xf bound_ctrl:1
	v_add_f32_dpp v39, v39, v39 row_half_mirror row_mask:0xf bank_mask:0xf bound_ctrl:1
	s_nop 0
	v_add_f32_dpp v38, v38, v38 row_mirror row_mask:0xf bank_mask:0xf bound_ctrl:1
	v_add_f32_dpp v39, v39, v39 row_mirror row_mask:0xf bank_mask:0xf bound_ctrl:1
	v_cvt_pk_bf16_f32 v47, v38, v39
	s_mov_b64 exec, s[2:3]
	global_store_dword v46, v47, s[14:15] offset:-4096
	s_mov_b64 exec, -1
	ds_read_b128 v[48:51], v22 offset:12288
	ds_read_b128 v[52:55], v22 offset:12544
	ds_read_b128 v[56:59], v22 offset:12800
	ds_read_b128 v[60:63], v22 offset:13056
	ds_read_b64 v[64:65], v23 offset:21504
	s_waitcnt lgkmcnt(5)
	v_pk_mul_f32 v[42:43], v[82:83], v[66:67] op_sel_hi:[1,0]
	v_pk_fma_f32 v[6:7], v[6:7], v[40:41], v[42:43] op_sel_hi:[1,0,1]
	v_pk_mul_f32 v[38:39], v[6:7], v[66:67] op_sel:[0,1] op_sel_hi:[1,1]
	v_pk_mul_f32 v[44:45], v[82:83], v[68:69] op_sel_hi:[1,0]
	v_pk_fma_f32 v[8:9], v[8:9], v[40:41], v[44:45] op_sel_hi:[1,0,1]
	v_pk_fma_f32 v[38:39], v[8:9], v[68:69], v[38:39] op_sel:[0,1,0] op_sel_hi:[1,1,1]
	v_pk_mul_f32 v[42:43], v[82:83], v[70:71] op_sel_hi:[1,0]
	v_pk_fma_f32 v[10:11], v[10:11], v[40:41], v[42:43] op_sel_hi:[1,0,1]
	v_pk_fma_f32 v[38:39], v[10:11], v[70:71], v[38:39] op_sel:[0,1,0] op_sel_hi:[1,1,1]
	v_pk_mul_f32 v[44:45], v[82:83], v[72:73] op_sel_hi:[1,0]
	v_pk_fma_f32 v[12:13], v[12:13], v[40:41], v[44:45] op_sel_hi:[1,0,1]
	v_pk_fma_f32 v[38:39], v[12:13], v[72:73], v[38:39] op_sel:[0,1,0] op_sel_hi:[1,1,1]
	v_pk_mul_f32 v[42:43], v[82:83], v[74:75] op_sel_hi:[1,0]
	v_pk_fma_f32 v[14:15], v[14:15], v[40:41], v[42:43] op_sel_hi:[1,0,1]
	v_pk_fma_f32 v[38:39], v[14:15], v[74:75], v[38:39] op_sel:[0,1,0] op_sel_hi:[1,1,1]
	v_pk_mul_f32 v[44:45], v[82:83], v[76:77] op_sel_hi:[1,0]
	v_pk_fma_f32 v[16:17], v[16:17], v[40:41], v[44:45] op_sel_hi:[1,0,1]
	v_pk_fma_f32 v[38:39], v[16:17], v[76:77], v[38:39] op_sel:[0,1,0] op_sel_hi:[1,1,1]
	v_pk_mul_f32 v[42:43], v[82:83], v[78:79] op_sel_hi:[1,0]
	v_pk_fma_f32 v[18:19], v[18:19], v[40:41], v[42:43] op_sel_hi:[1,0,1]
	v_pk_fma_f32 v[38:39], v[18:19], v[78:79], v[38:39] op_sel:[0,1,0] op_sel_hi:[1,1,1]
	v_pk_mul_f32 v[44:45], v[82:83], v[80:81] op_sel_hi:[1,0]
	v_pk_fma_f32 v[20:21], v[20:21], v[40:41], v[44:45] op_sel_hi:[1,0,1]
	v_pk_fma_f32 v[38:39], v[20:21], v[80:81], v[38:39] op_sel:[0,1,0] op_sel_hi:[1,1,1]
	s_add_u32 s14, s14, 0x1000
	s_addc_u32 s15, s15, 0
	v_add_f32_dpp v38, v38, v38 quad_perm:[1,0,3,2] row_mask:0xf bank_mask:0xf bound_ctrl:1
	v_add_f32_dpp v39, v39, v39 quad_perm:[1,0,3,2] row_mask:0xf bank_mask:0xf bound_ctrl:1
	s_nop 0
	v_add_f32_dpp v38, v38, v38 quad_perm:[2,3,0,1] row_mask:0xf bank_mask:0xf bound_ctrl:1
	v_add_f32_dpp v39, v39, v39 quad_perm:[2,3,0,1] row_mask:0xf bank_mask:0xf bound_ctrl:1
	s_nop 0
	v_add_f32_dpp v38, v38, v38 row_half_mirror row_mask:0xf bank_mask:0xf bound_ctrl:1
	v_add_f32_dpp v39, v39, v39 row_half_mirror row_mask:0xf bank_mask:0xf bound_ctrl:1
	s_nop 0
	v_add_f32_dpp v38, v38, v38 row_mirror row_mask:0xf bank_mask:0xf bound_ctrl:1
	v_add_f32_dpp v39, v39, v39 row_mirror row_mask:0xf bank_mask:0xf bound_ctrl:1
	v_cvt_pk_bf16_f32 v47, v38, v39
	s_mov_b64 exec, s[2:3]
	global_store_dword v46, v47, s[14:15] offset:-4096
	s_mov_b64 exec, -1
	ds_read_b128 v[66:69], v22 offset:13312
	ds_read_b128 v[70:73], v22 offset:13568
	ds_read_b128 v[74:77], v22 offset:13824
	ds_read_b128 v[78:81], v22 offset:14080
	ds_read_b64 v[82:83], v23 offset:21760
	s_waitcnt lgkmcnt(5)
	v_pk_mul_f32 v[42:43], v[64:65], v[48:49] op_sel_hi:[1,0]
	v_pk_fma_f32 v[6:7], v[6:7], v[40:41], v[42:43] op_sel_hi:[1,0,1]
	v_pk_mul_f32 v[38:39], v[6:7], v[48:49] op_sel:[0,1] op_sel_hi:[1,1]
	v_pk_mul_f32 v[44:45], v[64:65], v[50:51] op_sel_hi:[1,0]
	v_pk_fma_f32 v[8:9], v[8:9], v[40:41], v[44:45] op_sel_hi:[1,0,1]
	v_pk_fma_f32 v[38:39], v[8:9], v[50:51], v[38:39] op_sel:[0,1,0] op_sel_hi:[1,1,1]
	v_pk_mul_f32 v[42:43], v[64:65], v[52:53] op_sel_hi:[1,0]
	v_pk_fma_f32 v[10:11], v[10:11], v[40:41], v[42:43] op_sel_hi:[1,0,1]
	v_pk_fma_f32 v[38:39], v[10:11], v[52:53], v[38:39] op_sel:[0,1,0] op_sel_hi:[1,1,1]
	v_pk_mul_f32 v[44:45], v[64:65], v[54:55] op_sel_hi:[1,0]
	v_pk_fma_f32 v[12:13], v[12:13], v[40:41], v[44:45] op_sel_hi:[1,0,1]
	v_pk_fma_f32 v[38:39], v[12:13], v[54:55], v[38:39] op_sel:[0,1,0] op_sel_hi:[1,1,1]
	v_pk_mul_f32 v[42:43], v[64:65], v[56:57] op_sel_hi:[1,0]
	v_pk_fma_f32 v[14:15], v[14:15], v[40:41], v[42:43] op_sel_hi:[1,0,1]
	v_pk_fma_f32 v[38:39], v[14:15], v[56:57], v[38:39] op_sel:[0,1,0] op_sel_hi:[1,1,1]
	v_pk_mul_f32 v[44:45], v[64:65], v[58:59] op_sel_hi:[1,0]
	v_pk_fma_f32 v[16:17], v[16:17], v[40:41], v[44:45] op_sel_hi:[1,0,1]
	v_pk_fma_f32 v[38:39], v[16:17], v[58:59], v[38:39] op_sel:[0,1,0] op_sel_hi:[1,1,1]
	v_pk_mul_f32 v[42:43], v[64:65], v[60:61] op_sel_hi:[1,0]
	v_pk_fma_f32 v[18:19], v[18:19], v[40:41], v[42:43] op_sel_hi:[1,0,1]
	v_pk_fma_f32 v[38:39], v[18:19], v[60:61], v[38:39] op_sel:[0,1,0] op_sel_hi:[1,1,1]
	v_pk_mul_f32 v[44:45], v[64:65], v[62:63] op_sel_hi:[1,0]
	v_pk_fma_f32 v[20:21], v[20:21], v[40:41], v[44:45] op_sel_hi:[1,0,1]
	v_pk_fma_f32 v[38:39], v[20:21], v[62:63], v[38:39] op_sel:[0,1,0] op_sel_hi:[1,1,1]
	s_add_u32 s14, s14, 0x1000
	s_addc_u32 s15, s15, 0
	v_add_f32_dpp v38, v38, v38 quad_perm:[1,0,3,2] row_mask:0xf bank_mask:0xf bound_ctrl:1
	v_add_f32_dpp v39, v39, v39 quad_perm:[1,0,3,2] row_mask:0xf bank_mask:0xf bound_ctrl:1
	s_nop 0
	v_add_f32_dpp v38, v38, v38 quad_perm:[2,3,0,1] row_mask:0xf bank_mask:0xf bound_ctrl:1
	v_add_f32_dpp v39, v39, v39 quad_perm:[2,3,0,1] row_mask:0xf bank_mask:0xf bound_ctrl:1
	s_nop 0
	v_add_f32_dpp v38, v38, v38 row_half_mirror row_mask:0xf bank_mask:0xf bound_ctrl:1
	v_add_f32_dpp v39, v39, v39 row_half_mirror row_mask:0xf bank_mask:0xf bound_ctrl:1
	s_nop 0
	v_add_f32_dpp v38, v38, v38 row_mirror row_mask:0xf bank_mask:0xf bound_ctrl:1
	v_add_f32_dpp v39, v39, v39 row_mirror row_mask:0xf bank_mask:0xf bound_ctrl:1
	v_cvt_pk_bf16_f32 v47, v38, v39
	s_mov_b64 exec, s[2:3]
	global_store_dword v46, v47, s[14:15] offset:-4096
	s_mov_b64 exec, -1
	ds_read_b128 v[48:51], v22 offset:14336
	ds_read_b128 v[52:55], v22 offset:14592
	ds_read_b128 v[56:59], v22 offset:14848
	ds_read_b128 v[60:63], v22 offset:15104
	ds_read_b64 v[64:65], v23 offset:22016
	s_waitcnt lgkmcnt(5)
	v_pk_mul_f32 v[42:43], v[82:83], v[66:67] op_sel_hi:[1,0]
	v_pk_fma_f32 v[6:7], v[6:7], v[40:41], v[42:43] op_sel_hi:[1,0,1]
	v_pk_mul_f32 v[38:39], v[6:7], v[66:67] op_sel:[0,1] op_sel_hi:[1,1]
	v_pk_mul_f32 v[44:45], v[82:83], v[68:69] op_sel_hi:[1,0]
	v_pk_fma_f32 v[8:9], v[8:9], v[40:41], v[44:45] op_sel_hi:[1,0,1]
	v_pk_fma_f32 v[38:39], v[8:9], v[68:69], v[38:39] op_sel:[0,1,0] op_sel_hi:[1,1,1]
	v_pk_mul_f32 v[42:43], v[82:83], v[70:71] op_sel_hi:[1,0]
	v_pk_fma_f32 v[10:11], v[10:11], v[40:41], v[42:43] op_sel_hi:[1,0,1]
	v_pk_fma_f32 v[38:39], v[10:11], v[70:71], v[38:39] op_sel:[0,1,0] op_sel_hi:[1,1,1]
	v_pk_mul_f32 v[44:45], v[82:83], v[72:73] op_sel_hi:[1,0]
	v_pk_fma_f32 v[12:13], v[12:13], v[40:41], v[44:45] op_sel_hi:[1,0,1]
	v_pk_fma_f32 v[38:39], v[12:13], v[72:73], v[38:39] op_sel:[0,1,0] op_sel_hi:[1,1,1]
	v_pk_mul_f32 v[42:43], v[82:83], v[74:75] op_sel_hi:[1,0]
	v_pk_fma_f32 v[14:15], v[14:15], v[40:41], v[42:43] op_sel_hi:[1,0,1]
	v_pk_fma_f32 v[38:39], v[14:15], v[74:75], v[38:39] op_sel:[0,1,0] op_sel_hi:[1,1,1]
	v_pk_mul_f32 v[44:45], v[82:83], v[76:77] op_sel_hi:[1,0]
	v_pk_fma_f32 v[16:17], v[16:17], v[40:41], v[44:45] op_sel_hi:[1,0,1]
	v_pk_fma_f32 v[38:39], v[16:17], v[76:77], v[38:39] op_sel:[0,1,0] op_sel_hi:[1,1,1]
	v_pk_mul_f32 v[42:43], v[82:83], v[78:79] op_sel_hi:[1,0]
	v_pk_fma_f32 v[18:19], v[18:19], v[40:41], v[42:43] op_sel_hi:[1,0,1]
	v_pk_fma_f32 v[38:39], v[18:19], v[78:79], v[38:39] op_sel:[0,1,0] op_sel_hi:[1,1,1]
	v_pk_mul_f32 v[44:45], v[82:83], v[80:81] op_sel_hi:[1,0]
	v_pk_fma_f32 v[20:21], v[20:21], v[40:41], v[44:45] op_sel_hi:[1,0,1]
	v_pk_fma_f32 v[38:39], v[20:21], v[80:81], v[38:39] op_sel:[0,1,0] op_sel_hi:[1,1,1]
	s_add_u32 s14, s14, 0x1000
	s_addc_u32 s15, s15, 0
	v_add_f32_dpp v38, v38, v38 quad_perm:[1,0,3,2] row_mask:0xf bank_mask:0xf bound_ctrl:1
	v_add_f32_dpp v39, v39, v39 quad_perm:[1,0,3,2] row_mask:0xf bank_mask:0xf bound_ctrl:1
	s_nop 0
	v_add_f32_dpp v38, v38, v38 quad_perm:[2,3,0,1] row_mask:0xf bank_mask:0xf bound_ctrl:1
	v_add_f32_dpp v39, v39, v39 quad_perm:[2,3,0,1] row_mask:0xf bank_mask:0xf bound_ctrl:1
	s_nop 0
	v_add_f32_dpp v38, v38, v38 row_half_mirror row_mask:0xf bank_mask:0xf bound_ctrl:1
	v_add_f32_dpp v39, v39, v39 row_half_mirror row_mask:0xf bank_mask:0xf bound_ctrl:1
	s_nop 0
	v_add_f32_dpp v38, v38, v38 row_mirror row_mask:0xf bank_mask:0xf bound_ctrl:1
	v_add_f32_dpp v39, v39, v39 row_mirror row_mask:0xf bank_mask:0xf bound_ctrl:1
	v_cvt_pk_bf16_f32 v47, v38, v39
	s_mov_b64 exec, s[2:3]
	global_store_dword v46, v47, s[14:15] offset:-4096
	s_mov_b64 exec, -1
	ds_read_b128 v[66:69], v22 offset:15360
	ds_read_b128 v[70:73], v22 offset:15616
	ds_read_b128 v[74:77], v22 offset:15872
	ds_read_b128 v[78:81], v22 offset:16128
	ds_read_b64 v[82:83], v23 offset:22272
	s_waitcnt lgkmcnt(5)
	v_pk_mul_f32 v[42:43], v[64:65], v[48:49] op_sel_hi:[1,0]
	v_pk_fma_f32 v[6:7], v[6:7], v[40:41], v[42:43] op_sel_hi:[1,0,1]
	v_pk_mul_f32 v[38:39], v[6:7], v[48:49] op_sel:[0,1] op_sel_hi:[1,1]
	v_pk_mul_f32 v[44:45], v[64:65], v[50:51] op_sel_hi:[1,0]
	v_pk_fma_f32 v[8:9], v[8:9], v[40:41], v[44:45] op_sel_hi:[1,0,1]
	v_pk_fma_f32 v[38:39], v[8:9], v[50:51], v[38:39] op_sel:[0,1,0] op_sel_hi:[1,1,1]
	v_pk_mul_f32 v[42:43], v[64:65], v[52:53] op_sel_hi:[1,0]
	v_pk_fma_f32 v[10:11], v[10:11], v[40:41], v[42:43] op_sel_hi:[1,0,1]
	v_pk_fma_f32 v[38:39], v[10:11], v[52:53], v[38:39] op_sel:[0,1,0] op_sel_hi:[1,1,1]
	v_pk_mul_f32 v[44:45], v[64:65], v[54:55] op_sel_hi:[1,0]
	v_pk_fma_f32 v[12:13], v[12:13], v[40:41], v[44:45] op_sel_hi:[1,0,1]
	v_pk_fma_f32 v[38:39], v[12:13], v[54:55], v[38:39] op_sel:[0,1,0] op_sel_hi:[1,1,1]
	v_pk_mul_f32 v[42:43], v[64:65], v[56:57] op_sel_hi:[1,0]
	v_pk_fma_f32 v[14:15], v[14:15], v[40:41], v[42:43] op_sel_hi:[1,0,1]
	v_pk_fma_f32 v[38:39], v[14:15], v[56:57], v[38:39] op_sel:[0,1,0] op_sel_hi:[1,1,1]
	v_pk_mul_f32 v[44:45], v[64:65], v[58:59] op_sel_hi:[1,0]
	v_pk_fma_f32 v[16:17], v[16:17], v[40:41], v[44:45] op_sel_hi:[1,0,1]
	v_pk_fma_f32 v[38:39], v[16:17], v[58:59], v[38:39] op_sel:[0,1,0] op_sel_hi:[1,1,1]
	v_pk_mul_f32 v[42:43], v[64:65], v[60:61] op_sel_hi:[1,0]
	v_pk_fma_f32 v[18:19], v[18:19], v[40:41], v[42:43] op_sel_hi:[1,0,1]
	v_pk_fma_f32 v[38:39], v[18:19], v[60:61], v[38:39] op_sel:[0,1,0] op_sel_hi:[1,1,1]
	v_pk_mul_f32 v[44:45], v[64:65], v[62:63] op_sel_hi:[1,0]
	v_pk_fma_f32 v[20:21], v[20:21], v[40:41], v[44:45] op_sel_hi:[1,0,1]
	v_pk_fma_f32 v[38:39], v[20:21], v[62:63], v[38:39] op_sel:[0,1,0] op_sel_hi:[1,1,1]
	s_add_u32 s14, s14, 0x1000
	s_addc_u32 s15, s15, 0
	v_add_f32_dpp v38, v38, v38 quad_perm:[1,0,3,2] row_mask:0xf bank_mask:0xf bound_ctrl:1
	v_add_f32_dpp v39, v39, v39 quad_perm:[1,0,3,2] row_mask:0xf bank_mask:0xf bound_ctrl:1
	s_nop 0
	v_add_f32_dpp v38, v38, v38 quad_perm:[2,3,0,1] row_mask:0xf bank_mask:0xf bound_ctrl:1
	v_add_f32_dpp v39, v39, v39 quad_perm:[2,3,0,1] row_mask:0xf bank_mask:0xf bound_ctrl:1
	s_nop 0
	v_add_f32_dpp v38, v38, v38 row_half_mirror row_mask:0xf bank_mask:0xf bound_ctrl:1
	v_add_f32_dpp v39, v39, v39 row_half_mirror row_mask:0xf bank_mask:0xf bound_ctrl:1
	s_nop 0
	v_add_f32_dpp v38, v38, v38 row_mirror row_mask:0xf bank_mask:0xf bound_ctrl:1
	v_add_f32_dpp v39, v39, v39 row_mirror row_mask:0xf bank_mask:0xf bound_ctrl:1
	v_cvt_pk_bf16_f32 v47, v38, v39
	s_mov_b64 exec, s[2:3]
	global_store_dword v46, v47, s[14:15] offset:-4096
	s_mov_b64 exec, -1
	ds_read_b128 v[48:51], v24 offset:8192
	ds_read_b128 v[52:55], v24 offset:8448
	ds_read_b128 v[56:59], v24 offset:8704
	ds_read_b128 v[60:63], v24 offset:8960
	ds_read_b64 v[64:65], v25 offset:20480
	s_waitcnt lgkmcnt(5)
	v_pk_mul_f32 v[42:43], v[82:83], v[66:67] op_sel_hi:[1,0]
	v_pk_fma_f32 v[6:7], v[6:7], v[40:41], v[42:43] op_sel_hi:[1,0,1]
	v_pk_mul_f32 v[38:39], v[6:7], v[66:67] op_sel:[0,1] op_sel_hi:[1,1]
	v_pk_mul_f32 v[44:45], v[82:83], v[68:69] op_sel_hi:[1,0]
	v_pk_fma_f32 v[8:9], v[8:9], v[40:41], v[44:45] op_sel_hi:[1,0,1]
	v_pk_fma_f32 v[38:39], v[8:9], v[68:69], v[38:39] op_sel:[0,1,0] op_sel_hi:[1,1,1]
	v_pk_mul_f32 v[42:43], v[82:83], v[70:71] op_sel_hi:[1,0]
	v_pk_fma_f32 v[10:11], v[10:11], v[40:41], v[42:43] op_sel_hi:[1,0,1]
	v_pk_fma_f32 v[38:39], v[10:11], v[70:71], v[38:39] op_sel:[0,1,0] op_sel_hi:[1,1,1]
	v_pk_mul_f32 v[44:45], v[82:83], v[72:73] op_sel_hi:[1,0]
	v_pk_fma_f32 v[12:13], v[12:13], v[40:41], v[44:45] op_sel_hi:[1,0,1]
	v_pk_fma_f32 v[38:39], v[12:13], v[72:73], v[38:39] op_sel:[0,1,0] op_sel_hi:[1,1,1]
	v_pk_mul_f32 v[42:43], v[82:83], v[74:75] op_sel_hi:[1,0]
	v_pk_fma_f32 v[14:15], v[14:15], v[40:41], v[42:43] op_sel_hi:[1,0,1]
	v_pk_fma_f32 v[38:39], v[14:15], v[74:75], v[38:39] op_sel:[0,1,0] op_sel_hi:[1,1,1]
	v_pk_mul_f32 v[44:45], v[82:83], v[76:77] op_sel_hi:[1,0]
	v_pk_fma_f32 v[16:17], v[16:17], v[40:41], v[44:45] op_sel_hi:[1,0,1]
	v_pk_fma_f32 v[38:39], v[16:17], v[76:77], v[38:39] op_sel:[0,1,0] op_sel_hi:[1,1,1]
	v_pk_mul_f32 v[42:43], v[82:83], v[78:79] op_sel_hi:[1,0]
	v_pk_fma_f32 v[18:19], v[18:19], v[40:41], v[42:43] op_sel_hi:[1,0,1]
	v_pk_fma_f32 v[38:39], v[18:19], v[78:79], v[38:39] op_sel:[0,1,0] op_sel_hi:[1,1,1]
	v_pk_mul_f32 v[44:45], v[82:83], v[80:81] op_sel_hi:[1,0]
	v_pk_fma_f32 v[20:21], v[20:21], v[40:41], v[44:45] op_sel_hi:[1,0,1]
	v_pk_fma_f32 v[38:39], v[20:21], v[80:81], v[38:39] op_sel:[0,1,0] op_sel_hi:[1,1,1]
	s_add_u32 s14, s14, 0x1000
	s_addc_u32 s15, s15, 0
	v_add_f32_dpp v38, v38, v38 quad_perm:[1,0,3,2] row_mask:0xf bank_mask:0xf bound_ctrl:1
	v_add_f32_dpp v39, v39, v39 quad_perm:[1,0,3,2] row_mask:0xf bank_mask:0xf bound_ctrl:1
	s_nop 0
	v_add_f32_dpp v38, v38, v38 quad_perm:[2,3,0,1] row_mask:0xf bank_mask:0xf bound_ctrl:1
	v_add_f32_dpp v39, v39, v39 quad_perm:[2,3,0,1] row_mask:0xf bank_mask:0xf bound_ctrl:1
	s_nop 0
	v_add_f32_dpp v38, v38, v38 row_half_mirror row_mask:0xf bank_mask:0xf bound_ctrl:1
	v_add_f32_dpp v39, v39, v39 row_half_mirror row_mask:0xf bank_mask:0xf bound_ctrl:1
	s_nop 0
	v_add_f32_dpp v38, v38, v38 row_mirror row_mask:0xf bank_mask:0xf bound_ctrl:1
	v_add_f32_dpp v39, v39, v39 row_mirror row_mask:0xf bank_mask:0xf bound_ctrl:1
	v_cvt_pk_bf16_f32 v47, v38, v39
	s_mov_b64 exec, s[2:3]
	global_store_dword v46, v47, s[14:15] offset:-4096
	s_mov_b64 exec, -1
	s_waitcnt vmcnt(8)
	v_lshlrev_b32_e32 v108, 16, v84
	v_lshlrev_b32_e32 v109, 16, v85
	v_and_b32_e32 v110, s17, v84
	v_and_b32_e32 v111, s17, v85
	v_lshlrev_b32_e32 v112, 16, v86
	v_lshlrev_b32_e32 v113, 16, v87
	v_and_b32_e32 v114, s17, v86
	v_and_b32_e32 v115, s17, v87
	v_lshlrev_b32_e32 v116, 16, v88
	v_and_b32_e32 v117, s17, v88
	ds_write_b128 v26, v[108:111] offset:0
	ds_write_b128 v26, v[112:115] offset:8192
	ds_write_b64 v27, v[90:91]
	ds_write_b64 v28, v[116:117]
	s_mov_b32 s0, s20
	s_mov_b32 s20, s21
	s_mov_b32 s21, s22
	s_mov_b32 s22, s0
	v_mov_b32_e32 v22, v24
	v_mov_b32_e32 v23, v25
	v_add_u32_e32 v24, s21, v2
	v_add_u32_e32 v25, s21, v3
	v_add_u32_e32 v26, s22, v29
	v_add_u32_e32 v27, s22, v30
	v_add_u32_e32 v28, s22, v31
	s_waitcnt lgkmcnt(0)
	s_barrier
	s_add_i32 s16, s16, 8
	s_cmpk_lt_u32 s16, 0x800
	s_cbranch_scc1 .Lret2_loop
	v_readlane_b32 s0, v255, 18
	v_readlane_b32 s1, v255, 19
	s_load_dwordx2 s[2:3], s[0:1], 0xe8
	s_lshr_b32 s0, s23, 5
	s_lshl_b32 s4, s0, 17
	s_add_u32 s4, s4, 78430464
	v_lshl_add_u32 v42, v46, 1, v4
	s_waitcnt lgkmcnt(0)
	s_add_u32 s2, s2, s4
	s_addc_u32 s3, s3, 0
	global_store_dwordx2 v42, v[6:7], s[2:3] offset:0
	global_store_dwordx2 v42, v[8:9], s[2:3] offset:1024
	global_store_dwordx2 v42, v[10:11], s[2:3] offset:2048
	global_store_dwordx2 v42, v[12:13], s[2:3] offset:3072
	s_add_u32 s2, s2, 0x1000
	s_addc_u32 s3, s3, 0
	global_store_dwordx2 v42, v[14:15], s[2:3] offset:0
	global_store_dwordx2 v42, v[16:17], s[2:3] offset:1024
	global_store_dwordx2 v42, v[18:19], s[2:3] offset:2048
	global_store_dwordx2 v42, v[20:21], s[2:3] offset:3072
	s_add_i32 s23, s23, s19
	s_waitcnt vmcnt(0)
	s_cmpk_lt_i32 s23, 0x400
	s_cbranch_scc1 .Lret2_item
	s_branch .LBB0_57

.LBB0_58:
	s_andn2_b64 vcc, exec, s[0:1]
	s_cbranch_vccnz .LBB0_80
	s_and_b64 vcc, exec, s[6:7]
	s_cbranch_vccnz .LBB0_80
	v_readlane_b32 s0, v255, 18
	v_readlane_b32 s1, v255, 19
	s_load_dwordx2 s[8:9], s[0:1], 0xf0
	v_readlane_b32 s5, v255, 15
	v_and_b32_e32 v46, 15, v198
	v_lshrrev_b32_e32 v5, 4, v198
	v_lshlrev_b32_e32 v2, 4, v46
	v_lshlrev_b32_e32 v4, 13, v46
	s_mov_b32 s17, 0xffff0000
	v_and_b32_e32 v42, 3, v198
	v_lshrrev_b32_e32 v44, 2, v198
	v_lshlrev_b32_e32 v29, 8, v42
	v_lshl_add_u32 v29, v44, 4, v29
	s_lshl_b32 s0, s5, 10
	v_add_u32_e32 v29, s0, v29
	v_lshrrev_b32_e32 v30, 1, v42
	v_lshlrev_b32_e32 v30, 8, v30
	v_lshl_add_u32 v30, v44, 4, v30
	v_and_b32_e32 v42, 1, v198
	v_lshl_add_u32 v30, v42, 3, v30
	s_lshl_b32 s0, s5, 9
	s_add_u32 s0, s0, 16384
	v_add_u32_e32 v30, s0, v30
	v_min_u32_e32 v42, 31, v198
	v_lshlrev_b32_e32 v31, 3, v42
	s_lshl_b32 s0, s5, 8
	s_add_u32 s0, s0, 20480
	v_add_u32_e32 v31, s0, v31
	v_lshlrev_b32_e32 v35, 3, v198
	s_waitcnt lgkmcnt(0)
.Lgla2_item:
	s_lshr_b32 s0, s18, 5
	s_and_b32 s1, s18, 31
	s_lshr_b32 s2, s0, 2
	s_and_b32 s3, s0, 3
	s_lshl_b32 s4, s1, 4
	v_lshl_add_u32 v46, v5, 2, s4
	s_and_b32 s4, s1, 3
	s_lshl_b32 s4, s4, 5
	v_lshl_add_u32 v3, v5, 3, s4
	s_lshl_b32 s4, s3, 8
	s_add_u32 s4, s4, 1024
	v_lshl_add_u32 v32, v198, 2, s4
	s_add_u32 s4, s4, 4096
	v_lshl_add_u32 v33, v198, 2, s4
	s_lshl_b32 s4, s3, 9
	s_and_b32 s5, s1, 28
	s_lshl_b32 s5, s5, 4
	s_add_u32 s4, s4, s5
	s_add_u32 s4, s4, 2048
	v_min_u32_e32 v42, 31, v198
	v_lshl_add_u32 v34, v42, 2, s4
	v_cmp_lt_u32_e32 vcc, 15, v198
	v_add_u32_e32 v44, 4032, v34
	s_nop 1
	v_cndmask_b32_e32 v34, v34, v44, vcc
	v_readlane_b32 s5, v255, 15
	s_mul_i32 s4, s2, 0x1800000
	s_mul_i32 s1, s5, 0x3000
	s_add_u32 s4, s4, s1
	s_add_u32 s4, s4, 0x3bc0400
	s_add_u32 s10, s8, s4
	s_addc_u32 s11, s9, 0
	s_lshl_b32 s4, s2, 22
	s_lshl_b32 s1, s5, 11
	s_add_u32 s4, s4, s1
	s_lshl_b32 s1, s3, 9
	s_add_u32 s4, s4, s1
	s_add_u32 s4, s4, 0xfd40400
	s_add_u32 s12, s8, s4
	s_addc_u32 s13, s9, 0
	s_lshl_b32 s4, s2, 23
	s_add_u32 s4, s4, s1
	s_add_u32 s4, s4, 333186048
	s_add_u32 s14, s8, s4
	s_addc_u32 s15, s9, 0
	v_mov_b32_e32 v40, 0x3db504f3
	s_movk_i32 s20, 256
	s_movk_i32 s21, 24832
	s_mov_b32 s22, 49408
	v_add_u32_e32 v26, s20, v29
	v_add_u32_e32 v27, s20, v30
	v_add_u32_e32 v28, s20, v31
	global_load_dword v110, v32, s[10:11]
	global_load_dword v111, v32, s[10:11] offset:-1024
	global_load_dword v112, v33, s[10:11]
	global_load_dword v113, v33, s[10:11] offset:-1024
	global_load_dword v114, v34, s[10:11]
	global_load_dword v116, v35, s[12:13]
	global_load_dword v117, v35, s[12:13] offset:4
	s_add_u32 s10, s10, 0x18000
	s_addc_u32 s11, s11, 0
	s_add_u32 s12, s12, 0x4000
	s_addc_u32 s13, s13, 0
	s_waitcnt vmcnt(0)
	v_lshlrev_b32_e32 v144, 16, v110
	v_lshlrev_b32_e32 v145, 16, v111
	v_and_b32_e32 v146, s17, v110
	v_and_b32_e32 v147, s17, v111
	v_lshlrev_b32_e32 v148, 16, v112
	v_lshlrev_b32_e32 v149, 16, v113
	v_and_b32_e32 v150, s17, v112
	v_and_b32_e32 v151, s17, v113
	v_lshlrev_b32_e32 v152, 16, v114
	v_and_b32_e32 v153, s17, v114
	ds_write_b128 v26, v[144:147] offset:0
	ds_write_b128 v26, v[148:151] offset:8192
	ds_write_b64 v27, v[116:117]
	ds_write_b64 v28, v[152:153]
	v_add_u32_e32 v26, s21, v29
	v_add_u32_e32 v27, s21, v30
	v_add_u32_e32 v28, s21, v31
	global_load_dword v110, v32, s[10:11]
	global_load_dword v111, v32, s[10:11] offset:-1024
	global_load_dword v112, v33, s[10:11]
	global_load_dword v113, v33, s[10:11] offset:-1024
	global_load_dword v114, v34, s[10:11]
	global_load_dword v116, v35, s[12:13]
	global_load_dword v117, v35, s[12:13] offset:4
	s_add_u32 s10, s10, 0x18000
	s_addc_u32 s11, s11, 0
	s_add_u32 s12, s12, 0x4000
	s_addc_u32 s13, s13, 0
	s_waitcnt vmcnt(0)
	v_lshlrev_b32_e32 v144, 16, v110
	v_lshlrev_b32_e32 v145, 16, v111
	v_and_b32_e32 v146, s17, v110
	v_and_b32_e32 v147, s17, v111
	v_lshlrev_b32_e32 v148, 16, v112
	v_lshlrev_b32_e32 v149, 16, v113
	v_and_b32_e32 v150, s17, v112
	v_and_b32_e32 v151, s17, v113
	v_lshlrev_b32_e32 v152, 16, v114
	v_and_b32_e32 v153, s17, v114
	ds_write_b128 v26, v[144:147] offset:0
	ds_write_b128 v26, v[148:151] offset:8192
	ds_write_b64 v27, v[116:117]
	ds_write_b64 v28, v[152:153]
	v_add_u32_e32 v26, s22, v29
	v_add_u32_e32 v27, s22, v30
	v_add_u32_e32 v28, s22, v31
	v_add_u32_e32 v22, s20, v2
	v_add_u32_e32 v23, s20, v3
	v_add_u32_e32 v24, s21, v2
	v_add_u32_e32 v25, s21, v3
	v_mov_b32_e32 v6, 0
	v_mov_b32_e32 v7, 0
	v_mov_b32_e32 v8, 0
	v_mov_b32_e32 v9, 0
	v_mov_b32_e32 v10, 0
	v_mov_b32_e32 v11, 0
	v_mov_b32_e32 v12, 0
	v_mov_b32_e32 v13, 0
	v_mov_b32_e32 v14, 0
	v_mov_b32_e32 v15, 0
	v_mov_b32_e32 v16, 0
	v_mov_b32_e32 v17, 0
	v_mov_b32_e32 v18, 0
	v_mov_b32_e32 v19, 0
	v_mov_b32_e32 v20, 0
	v_mov_b32_e32 v21, 0
	s_mov_b32 s16, 0
	s_mov_b32 s2, 0x10001
	s_mov_b32 s3, 0x10001
	s_waitcnt vmcnt(0) lgkmcnt(0)
	s_barrier
	ds_read_b128 v[48:51], v22 offset:0
	ds_read_b128 v[52:55], v22 offset:256
	ds_read_b128 v[56:59], v22 offset:512
	ds_read_b128 v[60:63], v22 offset:768
	ds_read_b128 v[64:67], v22 offset:16384
	ds_read_b128 v[68:71], v22 offset:16640
	ds_read_b64 v[72:73], v23 offset:20480
.Lgla2_loop:
	global_load_dword v110, v32, s[10:11]
	global_load_dword v111, v32, s[10:11] offset:-1024
	global_load_dword v112, v33, s[10:11]
	global_load_dword v113, v33, s[10:11] offset:-1024
	global_load_dword v114, v34, s[10:11]
	global_load_dword v116, v35, s[12:13]
	global_load_dword v117, v35, s[12:13] offset:4
	s_add_u32 s10, s10, 0x18000
	s_addc_u32 s11, s11, 0
	s_add_u32 s12, s12, 0x4000
	s_addc_u32 s13, s13, 0
	ds_read_b128 v[80:83], v22 offset:1024
	ds_read_b128 v[84:87], v22 offset:1280
	ds_read_b128 v[88:91], v22 offset:1536
	ds_read_b128 v[92:95], v22 offset:1792
	ds_read_b128 v[96:99], v22 offset:16896
	ds_read_b128 v[100:103], v22 offset:17152
	ds_read_b64 v[104:105], v23 offset:20736
	s_waitcnt lgkmcnt(7)
	v_pk_mul_f32 v[42:43], v[72:73], v[48:49] op_sel_hi:[1,0]
	v_pk_fma_f32 v[6:7], v[6:7], v[64:65], v[42:43] op_sel:[0,0,0] op_sel_hi:[1,0,1]
	v_pk_mul_f32 v[38:39], v[6:7], v[48:49] op_sel:[0,1] op_sel_hi:[1,1]
	v_pk_mul_f32 v[44:45], v[72:73], v[50:51] op_sel_hi:[1,0]
	v_pk_fma_f32 v[8:9], v[8:9], v[64:65], v[44:45] op_sel:[0,1,0] op_sel_hi:[1,1,1]
	v_pk_fma_f32 v[38:39], v[8:9], v[50:51], v[38:39] op_sel:[0,1,0] op_sel_hi:[1,1,1]
	v_pk_mul_f32 v[42:43], v[72:73], v[52:53] op_sel_hi:[1,0]
	v_pk_fma_f32 v[10:11], v[10:11], v[66:67], v[42:43] op_sel:[0,0,0] op_sel_hi:[1,0,1]
	v_pk_fma_f32 v[38:39], v[10:11], v[52:53], v[38:39] op_sel:[0,1,0] op_sel_hi:[1,1,1]
	v_pk_mul_f32 v[44:45], v[72:73], v[54:55] op_sel_hi:[1,0]
	v_pk_fma_f32 v[12:13], v[12:13], v[66:67], v[44:45] op_sel:[0,1,0] op_sel_hi:[1,1,1]
	v_pk_fma_f32 v[38:39], v[12:13], v[54:55], v[38:39] op_sel:[0,1,0] op_sel_hi:[1,1,1]
	v_pk_mul_f32 v[42:43], v[72:73], v[56:57] op_sel_hi:[1,0]
	v_pk_fma_f32 v[14:15], v[14:15], v[68:69], v[42:43] op_sel:[0,0,0] op_sel_hi:[1,0,1]
	v_pk_fma_f32 v[38:39], v[14:15], v[56:57], v[38:39] op_sel:[0,1,0] op_sel_hi:[1,1,1]
	v_pk_mul_f32 v[44:45], v[72:73], v[58:59] op_sel_hi:[1,0]
	v_pk_fma_f32 v[16:17], v[16:17], v[68:69], v[44:45] op_sel:[0,1,0] op_sel_hi:[1,1,1]
	v_pk_fma_f32 v[38:39], v[16:17], v[58:59], v[38:39] op_sel:[0,1,0] op_sel_hi:[1,1,1]
	v_pk_mul_f32 v[42:43], v[72:73], v[60:61] op_sel_hi:[1,0]
	v_pk_fma_f32 v[18:19], v[18:19], v[70:71], v[42:43] op_sel:[0,0,0] op_sel_hi:[1,0,1]
	v_pk_fma_f32 v[38:39], v[18:19], v[60:61], v[38:39] op_sel:[0,1,0] op_sel_hi:[1,1,1]
	v_pk_mul_f32 v[44:45], v[72:73], v[62:63] op_sel_hi:[1,0]
	v_pk_fma_f32 v[20:21], v[20:21], v[70:71], v[44:45] op_sel:[0,1,0] op_sel_hi:[1,1,1]
	v_pk_fma_f32 v[38:39], v[20:21], v[62:63], v[38:39] op_sel:[0,1,0] op_sel_hi:[1,1,1]
	s_add_u32 s14, s14, 0x1000
	s_addc_u32 s15, s15, 0
	v_add_f32_dpp v38, v38, v38 quad_perm:[1,0,3,2] row_mask:0xf bank_mask:0xf bound_ctrl:1
	v_add_f32_dpp v39, v39, v39 quad_perm:[1,0,3,2] row_mask:0xf bank_mask:0xf bound_ctrl:1
	s_nop 0
	v_add_f32_dpp v38, v38, v38 quad_perm:[2,3,0,1] row_mask:0xf bank_mask:0xf bound_ctrl:1
	v_add_f32_dpp v39, v39, v39 quad_perm:[2,3,0,1] row_mask:0xf bank_mask:0xf bound_ctrl:1
	s_nop 0
	v_add_f32_dpp v38, v38, v38 row_half_mirror row_mask:0xf bank_mask:0xf bound_ctrl:1
	v_add_f32_dpp v39, v39, v39 row_half_mirror row_mask:0xf bank_mask:0xf bound_ctrl:1
	s_nop 0
	v_add_f32_dpp v38, v38, v38 row_mirror row_mask:0xf bank_mask:0xf bound_ctrl:1
	v_add_f32_dpp v39, v39, v39 row_mirror row_mask:0xf bank_mask:0xf bound_ctrl:1
	v_pk_mul_f32 v[38:39], v[38:39], v[40:41] op_sel_hi:[1,0]
	v_cvt_pk_bf16_f32 v47, v38, v39
	s_mov_b64 exec, s[2:3]
	global_store_dword v46, v47, s[14:15] offset:-4096
	s_mov_b64 exec, -1
	ds_read_b128 v[48:51], v22 offset:2048
	ds_read_b128 v[52:55], v22 offset:2304
	ds_read_b128 v[56:59], v22 offset:2560
	ds_read_b128 v[60:63], v22 offset:2816
	ds_read_b128 v[64:67], v22 offset:17408
	ds_read_b128 v[68:71], v22 offset:17664
	ds_read_b64 v[72:73], v23 offset:20992
	s_waitcnt lgkmcnt(7)
	v_pk_mul_f32 v[42:43], v[104:105], v[80:81] op_sel_hi:[1,0]
	v_pk_fma_f32 v[6:7], v[6:7], v[96:97], v[42:43] op_sel:[0,0,0] op_sel_hi:[1,0,1]
	v_pk_mul_f32 v[38:39], v[6:7], v[80:81] op_sel:[0,1] op_sel_hi:[1,1]
	v_pk_mul_f32 v[44:45], v[104:105], v[82:83] op_sel_hi:[1,0]
	v_pk_fma_f32 v[8:9], v[8:9], v[96:97], v[44:45] op_sel:[0,1,0] op_sel_hi:[1,1,1]
	v_pk_fma_f32 v[38:39], v[8:9], v[82:83], v[38:39] op_sel:[0,1,0] op_sel_hi:[1,1,1]
	v_pk_mul_f32 v[42:43], v[104:105], v[84:85] op_sel_hi:[1,0]
	v_pk_fma_f32 v[10:11], v[10:11], v[98:99], v[42:43] op_sel:[0,0,0] op_sel_hi:[1,0,1]
	v_pk_fma_f32 v[38:39], v[10:11], v[84:85], v[38:39] op_sel:[0,1,0] op_sel_hi:[1,1,1]
	v_pk_mul_f32 v[44:45], v[104:105], v[86:87] op_sel_hi:[1,0]
	v_pk_fma_f32 v[12:13], v[12:13], v[98:99], v[44:45] op_sel:[0,1,0] op_sel_hi:[1,1,1]
	v_pk_fma_f32 v[38:39], v[12:13], v[86:87], v[38:39] op_sel:[0,1,0] op_sel_hi:[1,1,1]
	v_pk_mul_f32 v[42:43], v[104:105], v[88:89] op_sel_hi:[1,0]
	v_pk_fma_f32 v[14:15], v[14:15], v[100:101], v[42:43] op_sel:[0,0,0] op_sel_hi:[1,0,1]
	v_pk_fma_f32 v[38:39], v[14:15], v[88:89], v[38:39] op_sel:[0,1,0] op_sel_hi:[1,1,1]
	v_pk_mul_f32 v[44:45], v[104:105], v[90:91] op_sel_hi:[1,0]
	v_pk_fma_f32 v[16:17], v[16:17], v[100:101], v[44:45] op_sel:[0,1,0] op_sel_hi:[1,1,1]
	v_pk_fma_f32 v[38:39], v[16:17], v[90:91], v[38:39] op_sel:[0,1,0] op_sel_hi:[1,1,1]
	v_pk_mul_f32 v[42:43], v[104:105], v[92:93] op_sel_hi:[1,0]
	v_pk_fma_f32 v[18:19], v[18:19], v[102:103], v[42:43] op_sel:[0,0,0] op_sel_hi:[1,0,1]
	v_pk_fma_f32 v[38:39], v[18:19], v[92:93], v[38:39] op_sel:[0,1,0] op_sel_hi:[1,1,1]
	v_pk_mul_f32 v[44:45], v[104:105], v[94:95] op_sel_hi:[1,0]
	v_pk_fma_f32 v[20:21], v[20:21], v[102:103], v[44:45] op_sel:[0,1,0] op_sel_hi:[1,1,1]
	v_pk_fma_f32 v[38:39], v[20:21], v[94:95], v[38:39] op_sel:[0,1,0] op_sel_hi:[1,1,1]
	s_add_u32 s14, s14, 0x1000
	s_addc_u32 s15, s15, 0
	v_add_f32_dpp v38, v38, v38 quad_perm:[1,0,3,2] row_mask:0xf bank_mask:0xf bound_ctrl:1
	v_add_f32_dpp v39, v39, v39 quad_perm:[1,0,3,2] row_mask:0xf bank_mask:0xf bound_ctrl:1
	s_nop 0
	v_add_f32_dpp v38, v38, v38 quad_perm:[2,3,0,1] row_mask:0xf bank_mask:0xf bound_ctrl:1
	v_add_f32_dpp v39, v39, v39 quad_perm:[2,3,0,1] row_mask:0xf bank_mask:0xf bound_ctrl:1
	s_nop 0
	v_add_f32_dpp v38, v38, v38 row_half_mirror row_mask:0xf bank_mask:0xf bound_ctrl:1
	v_add_f32_dpp v39, v39, v39 row_half_mirror row_mask:0xf bank_mask:0xf bound_ctrl:1
	s_nop 0
	v_add_f32_dpp v38, v38, v38 row_mirror row_mask:0xf bank_mask:0xf bound_ctrl:1
	v_add_f32_dpp v39, v39, v39 row_mirror row_mask:0xf bank_mask:0xf bound_ctrl:1
	v_pk_mul_f32 v[38:39], v[38:39], v[40:41] op_sel_hi:[1,0]
	v_cvt_pk_bf16_f32 v47, v38, v39
	s_mov_b64 exec, s[2:3]
	global_store_dword v46, v47, s[14:15] offset:-4096
	s_mov_b64 exec, -1
	ds_read_b128 v[80:83], v22 offset:3072
	ds_read_b128 v[84:87], v22 offset:3328
	ds_read_b128 v[88:91], v22 offset:3584
	ds_read_b128 v[92:95], v22 offset:3840
	ds_read_b128 v[96:99], v22 offset:17920
	ds_read_b128 v[100:103], v22 offset:18176
	ds_read_b64 v[104:105], v23 offset:21248
	s_waitcnt lgkmcnt(7)
	v_pk_mul_f32 v[42:43], v[72:73], v[48:49] op_sel_hi:[1,0]
	v_pk_fma_f32 v[6:7], v[6:7], v[64:65], v[42:43] op_sel:[0,0,0] op_sel_hi:[1,0,1]
	v_pk_mul_f32 v[38:39], v[6:7], v[48:49] op_sel:[0,1] op_sel_hi:[1,1]
	v_pk_mul_f32 v[44:45], v[72:73], v[50:51] op_sel_hi:[1,0]
	v_pk_fma_f32 v[8:9], v[8:9], v[64:65], v[44:45] op_sel:[0,1,0] op_sel_hi:[1,1,1]
	v_pk_fma_f32 v[38:39], v[8:9], v[50:51], v[38:39] op_sel:[0,1,0] op_sel_hi:[1,1,1]
	v_pk_mul_f32 v[42:43], v[72:73], v[52:53] op_sel_hi:[1,0]
	v_pk_fma_f32 v[10:11], v[10:11], v[66:67], v[42:43] op_sel:[0,0,0] op_sel_hi:[1,0,1]
	v_pk_fma_f32 v[38:39], v[10:11], v[52:53], v[38:39] op_sel:[0,1,0] op_sel_hi:[1,1,1]
	v_pk_mul_f32 v[44:45], v[72:73], v[54:55] op_sel_hi:[1,0]
	v_pk_fma_f32 v[12:13], v[12:13], v[66:67], v[44:45] op_sel:[0,1,0] op_sel_hi:[1,1,1]
	v_pk_fma_f32 v[38:39], v[12:13], v[54:55], v[38:39] op_sel:[0,1,0] op_sel_hi:[1,1,1]
	v_pk_mul_f32 v[42:43], v[72:73], v[56:57] op_sel_hi:[1,0]
	v_pk_fma_f32 v[14:15], v[14:15], v[68:69], v[42:43] op_sel:[0,0,0] op_sel_hi:[1,0,1]
	v_pk_fma_f32 v[38:39], v[14:15], v[56:57], v[38:39] op_sel:[0,1,0] op_sel_hi:[1,1,1]
	v_pk_mul_f32 v[44:45], v[72:73], v[58:59] op_sel_hi:[1,0]
	v_pk_fma_f32 v[16:17], v[16:17], v[68:69], v[44:45] op_sel:[0,1,0] op_sel_hi:[1,1,1]
	v_pk_fma_f32 v[38:39], v[16:17], v[58:59], v[38:39] op_sel:[0,1,0] op_sel_hi:[1,1,1]
	v_pk_mul_f32 v[42:43], v[72:73], v[60:61] op_sel_hi:[1,0]
	v_pk_fma_f32 v[18:19], v[18:19], v[70:71], v[42:43] op_sel:[0,0,0] op_sel_hi:[1,0,1]
	v_pk_fma_f32 v[38:39], v[18:19], v[60:61], v[38:39] op_sel:[0,1,0] op_sel_hi:[1,1,1]
	v_pk_mul_f32 v[44:45], v[72:73], v[62:63] op_sel_hi:[1,0]
	v_pk_fma_f32 v[20:21], v[20:21], v[70:71], v[44:45] op_sel:[0,1,0] op_sel_hi:[1,1,1]
	v_pk_fma_f32 v[38:39], v[20:21], v[62:63], v[38:39] op_sel:[0,1,0] op_sel_hi:[1,1,1]
	s_add_u32 s14, s14, 0x1000
	s_addc_u32 s15, s15, 0
	v_add_f32_dpp v38, v38, v38 quad_perm:[1,0,3,2] row_mask:0xf bank_mask:0xf bound_ctrl:1
	v_add_f32_dpp v39, v39, v39 quad_perm:[1,0,3,2] row_mask:0xf bank_mask:0xf bound_ctrl:1
	s_nop 0
	v_add_f32_dpp v38, v38, v38 quad_perm:[2,3,0,1] row_mask:0xf bank_mask:0xf bound_ctrl:1
	v_add_f32_dpp v39, v39, v39 quad_perm:[2,3,0,1] row_mask:0xf bank_mask:0xf bound_ctrl:1
	s_nop 0
	v_add_f32_dpp v38, v38, v38 row_half_mirror row_mask:0xf bank_mask:0xf bound_ctrl:1
	v_add_f32_dpp v39, v39, v39 row_half_mirror row_mask:0xf bank_mask:0xf bound_ctrl:1
	s_nop 0
	v_add_f32_dpp v38, v38, v38 row_mirror row_mask:0xf bank_mask:0xf bound_ctrl:1
	v_add_f32_dpp v39, v39, v39 row_mirror row_mask:0xf bank_mask:0xf bound_ctrl:1
	v_pk_mul_f32 v[38:39], v[38:39], v[40:41] op_sel_hi:[1,0]
	v_cvt_pk_bf16_f32 v47, v38, v39
	s_mov_b64 exec, s[2:3]
	global_store_dword v46, v47, s[14:15] offset:-4096
	s_mov_b64 exec, -1
	ds_read_b128 v[48:51], v22 offset:4096
	ds_read_b128 v[52:55], v22 offset:4352
	ds_read_b128 v[56:59], v22 offset:4608
	ds_read_b128 v[60:63], v22 offset:4864
	ds_read_b128 v[64:67], v22 offset:18432
	ds_read_b128 v[68:71], v22 offset:18688
	ds_read_b64 v[72:73], v23 offset:21504
	s_waitcnt lgkmcnt(7)
	v_pk_mul_f32 v[42:43], v[104:105], v[80:81] op_sel_hi:[1,0]
	v_pk_fma_f32 v[6:7], v[6:7], v[96:97], v[42:43] op_sel:[0,0,0] op_sel_hi:[1,0,1]
	v_pk_mul_f32 v[38:39], v[6:7], v[80:81] op_sel:[0,1] op_sel_hi:[1,1]
	v_pk_mul_f32 v[44:45], v[104:105], v[82:83] op_sel_hi:[1,0]
	v_pk_fma_f32 v[8:9], v[8:9], v[96:97], v[44:45] op_sel:[0,1,0] op_sel_hi:[1,1,1]
	v_pk_fma_f32 v[38:39], v[8:9], v[82:83], v[38:39] op_sel:[0,1,0] op_sel_hi:[1,1,1]
	v_pk_mul_f32 v[42:43], v[104:105], v[84:85] op_sel_hi:[1,0]
	v_pk_fma_f32 v[10:11], v[10:11], v[98:99], v[42:43] op_sel:[0,0,0] op_sel_hi:[1,0,1]
	v_pk_fma_f32 v[38:39], v[10:11], v[84:85], v[38:39] op_sel:[0,1,0] op_sel_hi:[1,1,1]
	v_pk_mul_f32 v[44:45], v[104:105], v[86:87] op_sel_hi:[1,0]
	v_pk_fma_f32 v[12:13], v[12:13], v[98:99], v[44:45] op_sel:[0,1,0] op_sel_hi:[1,1,1]
	v_pk_fma_f32 v[38:39], v[12:13], v[86:87], v[38:39] op_sel:[0,1,0] op_sel_hi:[1,1,1]
	v_pk_mul_f32 v[42:43], v[104:105], v[88:89] op_sel_hi:[1,0]
	v_pk_fma_f32 v[14:15], v[14:15], v[100:101], v[42:43] op_sel:[0,0,0] op_sel_hi:[1,0,1]
	v_pk_fma_f32 v[38:39], v[14:15], v[88:89], v[38:39] op_sel:[0,1,0] op_sel_hi:[1,1,1]
	v_pk_mul_f32 v[44:45], v[104:105], v[90:91] op_sel_hi:[1,0]
	v_pk_fma_f32 v[16:17], v[16:17], v[100:101], v[44:45] op_sel:[0,1,0] op_sel_hi:[1,1,1]
	v_pk_fma_f32 v[38:39], v[16:17], v[90:91], v[38:39] op_sel:[0,1,0] op_sel_hi:[1,1,1]
	v_pk_mul_f32 v[42:43], v[104:105], v[92:93] op_sel_hi:[1,0]
	v_pk_fma_f32 v[18:19], v[18:19], v[102:103], v[42:43] op_sel:[0,0,0] op_sel_hi:[1,0,1]
	v_pk_fma_f32 v[38:39], v[18:19], v[92:93], v[38:39] op_sel:[0,1,0] op_sel_hi:[1,1,1]
	v_pk_mul_f32 v[44:45], v[104:105], v[94:95] op_sel_hi:[1,0]
	v_pk_fma_f32 v[20:21], v[20:21], v[102:103], v[44:45] op_sel:[0,1,0] op_sel_hi:[1,1,1]
	v_pk_fma_f32 v[38:39], v[20:21], v[94:95], v[38:39] op_sel:[0,1,0] op_sel_hi:[1,1,1]
	s_add_u32 s14, s14, 0x1000
	s_addc_u32 s15, s15, 0
	v_add_f32_dpp v38, v38, v38 quad_perm:[1,0,3,2] row_mask:0xf bank_mask:0xf bound_ctrl:1
	v_add_f32_dpp v39, v39, v39 quad_perm:[1,0,3,2] row_mask:0xf bank_mask:0xf bound_ctrl:1
	s_nop 0
	v_add_f32_dpp v38, v38, v38 quad_perm:[2,3,0,1] row_mask:0xf bank_mask:0xf bound_ctrl:1
	v_add_f32_dpp v39, v39, v39 quad_perm:[2,3,0,1] row_mask:0xf bank_mask:0xf bound_ctrl:1
	s_nop 0
	v_add_f32_dpp v38, v38, v38 row_half_mirror row_mask:0xf bank_mask:0xf bound_ctrl:1
	v_add_f32_dpp v39, v39, v39 row_half_mirror row_mask:0xf bank_mask:0xf bound_ctrl:1
	s_nop 0
	v_add_f32_dpp v38, v38, v38 row_mirror row_mask:0xf bank_mask:0xf bound_ctrl:1
	v_add_f32_dpp v39, v39, v39 row_mirror row_mask:0xf bank_mask:0xf bound_ctrl:1
	v_pk_mul_f32 v[38:39], v[38:39], v[40:41] op_sel_hi:[1,0]
	v_cvt_pk_bf16_f32 v47, v38, v39
	s_mov_b64 exec, s[2:3]
	global_store_dword v46, v47, s[14:15] offset:-4096
	s_mov_b64 exec, -1
	ds_read_b128 v[80:83], v22 offset:5120
	ds_read_b128 v[84:87], v22 offset:5376
	ds_read_b128 v[88:91], v22 offset:5632
	ds_read_b128 v[92:95], v22 offset:5888
	ds_read_b128 v[96:99], v22 offset:18944
	ds_read_b128 v[100:103], v22 offset:19200
	ds_read_b64 v[104:105], v23 offset:21760
	s_waitcnt lgkmcnt(7)
	v_pk_mul_f32 v[42:43], v[72:73], v[48:49] op_sel_hi:[1,0]
	v_pk_fma_f32 v[6:7], v[6:7], v[64:65], v[42:43] op_sel:[0,0,0] op_sel_hi:[1,0,1]
	v_pk_mul_f32 v[38:39], v[6:7], v[48:49] op_sel:[0,1] op_sel_hi:[1,1]
	v_pk_mul_f32 v[44:45], v[72:73], v[50:51] op_sel_hi:[1,0]
	v_pk_fma_f32 v[8:9], v[8:9], v[64:65], v[44:45] op_sel:[0,1,0] op_sel_hi:[1,1,1]
	v_pk_fma_f32 v[38:39], v[8:9], v[50:51], v[38:39] op_sel:[0,1,0] op_sel_hi:[1,1,1]
	v_pk_mul_f32 v[42:43], v[72:73], v[52:53] op_sel_hi:[1,0]
	v_pk_fma_f32 v[10:11], v[10:11], v[66:67], v[42:43] op_sel:[0,0,0] op_sel_hi:[1,0,1]
	v_pk_fma_f32 v[38:39], v[10:11], v[52:53], v[38:39] op_sel:[0,1,0] op_sel_hi:[1,1,1]
	v_pk_mul_f32 v[44:45], v[72:73], v[54:55] op_sel_hi:[1,0]
	v_pk_fma_f32 v[12:13], v[12:13], v[66:67], v[44:45] op_sel:[0,1,0] op_sel_hi:[1,1,1]
	v_pk_fma_f32 v[38:39], v[12:13], v[54:55], v[38:39] op_sel:[0,1,0] op_sel_hi:[1,1,1]
	v_pk_mul_f32 v[42:43], v[72:73], v[56:57] op_sel_hi:[1,0]
	v_pk_fma_f32 v[14:15], v[14:15], v[68:69], v[42:43] op_sel:[0,0,0] op_sel_hi:[1,0,1]
	v_pk_fma_f32 v[38:39], v[14:15], v[56:57], v[38:39] op_sel:[0,1,0] op_sel_hi:[1,1,1]
	v_pk_mul_f32 v[44:45], v[72:73], v[58:59] op_sel_hi:[1,0]
	v_pk_fma_f32 v[16:17], v[16:17], v[68:69], v[44:45] op_sel:[0,1,0] op_sel_hi:[1,1,1]
	v_pk_fma_f32 v[38:39], v[16:17], v[58:59], v[38:39] op_sel:[0,1,0] op_sel_hi:[1,1,1]
	v_pk_mul_f32 v[42:43], v[72:73], v[60:61] op_sel_hi:[1,0]
	v_pk_fma_f32 v[18:19], v[18:19], v[70:71], v[42:43] op_sel:[0,0,0] op_sel_hi:[1,0,1]
	v_pk_fma_f32 v[38:39], v[18:19], v[60:61], v[38:39] op_sel:[0,1,0] op_sel_hi:[1,1,1]
	v_pk_mul_f32 v[44:45], v[72:73], v[62:63] op_sel_hi:[1,0]
	v_pk_fma_f32 v[20:21], v[20:21], v[70:71], v[44:45] op_sel:[0,1,0] op_sel_hi:[1,1,1]
	v_pk_fma_f32 v[38:39], v[20:21], v[62:63], v[38:39] op_sel:[0,1,0] op_sel_hi:[1,1,1]
	s_add_u32 s14, s14, 0x1000
	s_addc_u32 s15, s15, 0
	v_add_f32_dpp v38, v38, v38 quad_perm:[1,0,3,2] row_mask:0xf bank_mask:0xf bound_ctrl:1
	v_add_f32_dpp v39, v39, v39 quad_perm:[1,0,3,2] row_mask:0xf bank_mask:0xf bound_ctrl:1
	s_nop 0
	v_add_f32_dpp v38, v38, v38 quad_perm:[2,3,0,1] row_mask:0xf bank_mask:0xf bound_ctrl:1
	v_add_f32_dpp v39, v39, v39 quad_perm:[2,3,0,1] row_mask:0xf bank_mask:0xf bound_ctrl:1
	s_nop 0
	v_add_f32_dpp v38, v38, v38 row_half_mirror row_mask:0xf bank_mask:0xf bound_ctrl:1
	v_add_f32_dpp v39, v39, v39 row_half_mirror row_mask:0xf bank_mask:0xf bound_ctrl:1
	s_nop 0
	v_add_f32_dpp v38, v38, v38 row_mirror row_mask:0xf bank_mask:0xf bound_ctrl:1
	v_add_f32_dpp v39, v39, v39 row_mirror row_mask:0xf bank_mask:0xf bound_ctrl:1
	v_pk_mul_f32 v[38:39], v[38:39], v[40:41] op_sel_hi:[1,0]
	v_cvt_pk_bf16_f32 v47, v38, v39
	s_mov_b64 exec, s[2:3]
	global_store_dword v46, v47, s[14:15] offset:-4096
	s_mov_b64 exec, -1
	ds_read_b128 v[48:51], v22 offset:6144
	ds_read_b128 v[52:55], v22 offset:6400
	ds_read_b128 v[56:59], v22 offset:6656
	ds_read_b128 v[60:63], v22 offset:6912
	ds_read_b128 v[64:67], v22 offset:19456
	ds_read_b128 v[68:71], v22 offset:19712
	ds_read_b64 v[72:73], v23 offset:22016
	s_waitcnt lgkmcnt(7)
	v_pk_mul_f32 v[42:43], v[104:105], v[80:81] op_sel_hi:[1,0]
	v_pk_fma_f32 v[6:7], v[6:7], v[96:97], v[42:43] op_sel:[0,0,0] op_sel_hi:[1,0,1]
	v_pk_mul_f32 v[38:39], v[6:7], v[80:81] op_sel:[0,1] op_sel_hi:[1,1]
	v_pk_mul_f32 v[44:45], v[104:105], v[82:83] op_sel_hi:[1,0]
	v_pk_fma_f32 v[8:9], v[8:9], v[96:97], v[44:45] op_sel:[0,1,0] op_sel_hi:[1,1,1]
	v_pk_fma_f32 v[38:39], v[8:9], v[82:83], v[38:39] op_sel:[0,1,0] op_sel_hi:[1,1,1]
	v_pk_mul_f32 v[42:43], v[104:105], v[84:85] op_sel_hi:[1,0]
	v_pk_fma_f32 v[10:11], v[10:11], v[98:99], v[42:43] op_sel:[0,0,0] op_sel_hi:[1,0,1]
	v_pk_fma_f32 v[38:39], v[10:11], v[84:85], v[38:39] op_sel:[0,1,0] op_sel_hi:[1,1,1]
	v_pk_mul_f32 v[44:45], v[104:105], v[86:87] op_sel_hi:[1,0]
	v_pk_fma_f32 v[12:13], v[12:13], v[98:99], v[44:45] op_sel:[0,1,0] op_sel_hi:[1,1,1]
	v_pk_fma_f32 v[38:39], v[12:13], v[86:87], v[38:39] op_sel:[0,1,0] op_sel_hi:[1,1,1]
	v_pk_mul_f32 v[42:43], v[104:105], v[88:89] op_sel_hi:[1,0]
	v_pk_fma_f32 v[14:15], v[14:15], v[100:101], v[42:43] op_sel:[0,0,0] op_sel_hi:[1,0,1]
	v_pk_fma_f32 v[38:39], v[14:15], v[88:89], v[38:39] op_sel:[0,1,0] op_sel_hi:[1,1,1]
	v_pk_mul_f32 v[44:45], v[104:105], v[90:91] op_sel_hi:[1,0]
	v_pk_fma_f32 v[16:17], v[16:17], v[100:101], v[44:45] op_sel:[0,1,0] op_sel_hi:[1,1,1]
	v_pk_fma_f32 v[38:39], v[16:17], v[90:91], v[38:39] op_sel:[0,1,0] op_sel_hi:[1,1,1]
	v_pk_mul_f32 v[42:43], v[104:105], v[92:93] op_sel_hi:[1,0]
	v_pk_fma_f32 v[18:19], v[18:19], v[102:103], v[42:43] op_sel:[0,0,0] op_sel_hi:[1,0,1]
	v_pk_fma_f32 v[38:39], v[18:19], v[92:93], v[38:39] op_sel:[0,1,0] op_sel_hi:[1,1,1]
	v_pk_mul_f32 v[44:45], v[104:105], v[94:95] op_sel_hi:[1,0]
	v_pk_fma_f32 v[20:21], v[20:21], v[102:103], v[44:45] op_sel:[0,1,0] op_sel_hi:[1,1,1]
	v_pk_fma_f32 v[38:39], v[20:21], v[94:95], v[38:39] op_sel:[0,1,0] op_sel_hi:[1,1,1]
	s_add_u32 s14, s14, 0x1000
	s_addc_u32 s15, s15, 0
	v_add_f32_dpp v38, v38, v38 quad_perm:[1,0,3,2] row_mask:0xf bank_mask:0xf bound_ctrl:1
	v_add_f32_dpp v39, v39, v39 quad_perm:[1,0,3,2] row_mask:0xf bank_mask:0xf bound_ctrl:1
	s_nop 0
	v_add_f32_dpp v38, v38, v38 quad_perm:[2,3,0,1] row_mask:0xf bank_mask:0xf bound_ctrl:1
	v_add_f32_dpp v39, v39, v39 quad_perm:[2,3,0,1] row_mask:0xf bank_mask:0xf bound_ctrl:1
	s_nop 0
	v_add_f32_dpp v38, v38, v38 row_half_mirror row_mask:0xf bank_mask:0xf bound_ctrl:1
	v_add_f32_dpp v39, v39, v39 row_half_mirror row_mask:0xf bank_mask:0xf bound_ctrl:1
	s_nop 0
	v_add_f32_dpp v38, v38, v38 row_mirror row_mask:0xf bank_mask:0xf bound_ctrl:1
	v_add_f32_dpp v39, v39, v39 row_mirror row_mask:0xf bank_mask:0xf bound_ctrl:1
	v_pk_mul_f32 v[38:39], v[38:39], v[40:41] op_sel_hi:[1,0]
	v_cvt_pk_bf16_f32 v47, v38, v39
	s_mov_b64 exec, s[2:3]
	global_store_dword v46, v47, s[14:15] offset:-4096
	s_mov_b64 exec, -1
	ds_read_b128 v[80:83], v22 offset:7168
	ds_read_b128 v[84:87], v22 offset:7424
	ds_read_b128 v[88:91], v22 offset:7680
	ds_read_b128 v[92:95], v22 offset:7936
	ds_read_b128 v[96:99], v22 offset:19968
	ds_read_b128 v[100:103], v22 offset:20224
	ds_read_b64 v[104:105], v23 offset:22272
	s_waitcnt lgkmcnt(7)
	v_pk_mul_f32 v[42:43], v[72:73], v[48:49] op_sel_hi:[1,0]
	v_pk_fma_f32 v[6:7], v[6:7], v[64:65], v[42:43] op_sel:[0,0,0] op_sel_hi:[1,0,1]
	v_pk_mul_f32 v[38:39], v[6:7], v[48:49] op_sel:[0,1] op_sel_hi:[1,1]
	v_pk_mul_f32 v[44:45], v[72:73], v[50:51] op_sel_hi:[1,0]
	v_pk_fma_f32 v[8:9], v[8:9], v[64:65], v[44:45] op_sel:[0,1,0] op_sel_hi:[1,1,1]
	v_pk_fma_f32 v[38:39], v[8:9], v[50:51], v[38:39] op_sel:[0,1,0] op_sel_hi:[1,1,1]
	v_pk_mul_f32 v[42:43], v[72:73], v[52:53] op_sel_hi:[1,0]
	v_pk_fma_f32 v[10:11], v[10:11], v[66:67], v[42:43] op_sel:[0,0,0] op_sel_hi:[1,0,1]
	v_pk_fma_f32 v[38:39], v[10:11], v[52:53], v[38:39] op_sel:[0,1,0] op_sel_hi:[1,1,1]
	v_pk_mul_f32 v[44:45], v[72:73], v[54:55] op_sel_hi:[1,0]
	v_pk_fma_f32 v[12:13], v[12:13], v[66:67], v[44:45] op_sel:[0,1,0] op_sel_hi:[1,1,1]
	v_pk_fma_f32 v[38:39], v[12:13], v[54:55], v[38:39] op_sel:[0,1,0] op_sel_hi:[1,1,1]
	v_pk_mul_f32 v[42:43], v[72:73], v[56:57] op_sel_hi:[1,0]
	v_pk_fma_f32 v[14:15], v[14:15], v[68:69], v[42:43] op_sel:[0,0,0] op_sel_hi:[1,0,1]
	v_pk_fma_f32 v[38:39], v[14:15], v[56:57], v[38:39] op_sel:[0,1,0] op_sel_hi:[1,1,1]
	v_pk_mul_f32 v[44:45], v[72:73], v[58:59] op_sel_hi:[1,0]
	v_pk_fma_f32 v[16:17], v[16:17], v[68:69], v[44:45] op_sel:[0,1,0] op_sel_hi:[1,1,1]
	v_pk_fma_f32 v[38:39], v[16:17], v[58:59], v[38:39] op_sel:[0,1,0] op_sel_hi:[1,1,1]
	v_pk_mul_f32 v[42:43], v[72:73], v[60:61] op_sel_hi:[1,0]
	v_pk_fma_f32 v[18:19], v[18:19], v[70:71], v[42:43] op_sel:[0,0,0] op_sel_hi:[1,0,1]
	v_pk_fma_f32 v[38:39], v[18:19], v[60:61], v[38:39] op_sel:[0,1,0] op_sel_hi:[1,1,1]
	v_pk_mul_f32 v[44:45], v[72:73], v[62:63] op_sel_hi:[1,0]
	v_pk_fma_f32 v[20:21], v[20:21], v[70:71], v[44:45] op_sel:[0,1,0] op_sel_hi:[1,1,1]
	v_pk_fma_f32 v[38:39], v[20:21], v[62:63], v[38:39] op_sel:[0,1,0] op_sel_hi:[1,1,1]
	s_add_u32 s14, s14, 0x1000
	s_addc_u32 s15, s15, 0
	v_add_f32_dpp v38, v38, v38 quad_perm:[1,0,3,2] row_mask:0xf bank_mask:0xf bound_ctrl:1
	v_add_f32_dpp v39, v39, v39 quad_perm:[1,0,3,2] row_mask:0xf bank_mask:0xf bound_ctrl:1
	s_nop 0
	v_add_f32_dpp v38, v38, v38 quad_perm:[2,3,0,1] row_mask:0xf bank_mask:0xf bound_ctrl:1
	v_add_f32_dpp v39, v39, v39 quad_perm:[2,3,0,1] row_mask:0xf bank_mask:0xf bound_ctrl:1
	s_nop 0
	v_add_f32_dpp v38, v38, v38 row_half_mirror row_mask:0xf bank_mask:0xf bound_ctrl:1
	v_add_f32_dpp v39, v39, v39 row_half_mirror row_mask:0xf bank_mask:0xf bound_ctrl:1
	s_nop 0
	v_add_f32_dpp v38, v38, v38 row_mirror row_mask:0xf bank_mask:0xf bound_ctrl:1
	v_add_f32_dpp v39, v39, v39 row_mirror row_mask:0xf bank_mask:0xf bound_ctrl:1
	v_pk_mul_f32 v[38:39], v[38:39], v[40:41] op_sel_hi:[1,0]
	v_cvt_pk_bf16_f32 v47, v38, v39
	s_mov_b64 exec, s[2:3]
	global_store_dword v46, v47, s[14:15] offset:-4096
	s_mov_b64 exec, -1
	ds_read_b128 v[48:51], v24 offset:0
	ds_read_b128 v[52:55], v24 offset:256
	ds_read_b128 v[56:59], v24 offset:512
	ds_read_b128 v[60:63], v24 offset:768
	ds_read_b128 v[64:67], v24 offset:16384
	ds_read_b128 v[68:71], v24 offset:16640
	ds_read_b64 v[72:73], v25 offset:20480
	s_waitcnt lgkmcnt(7)
	v_pk_mul_f32 v[42:43], v[104:105], v[80:81] op_sel_hi:[1,0]
	v_pk_fma_f32 v[6:7], v[6:7], v[96:97], v[42:43] op_sel:[0,0,0] op_sel_hi:[1,0,1]
	v_pk_mul_f32 v[38:39], v[6:7], v[80:81] op_sel:[0,1] op_sel_hi:[1,1]
	v_pk_mul_f32 v[44:45], v[104:105], v[82:83] op_sel_hi:[1,0]
	v_pk_fma_f32 v[8:9], v[8:9], v[96:97], v[44:45] op_sel:[0,1,0] op_sel_hi:[1,1,1]
	v_pk_fma_f32 v[38:39], v[8:9], v[82:83], v[38:39] op_sel:[0,1,0] op_sel_hi:[1,1,1]
	v_pk_mul_f32 v[42:43], v[104:105], v[84:85] op_sel_hi:[1,0]
	v_pk_fma_f32 v[10:11], v[10:11], v[98:99], v[42:43] op_sel:[0,0,0] op_sel_hi:[1,0,1]
	v_pk_fma_f32 v[38:39], v[10:11], v[84:85], v[38:39] op_sel:[0,1,0] op_sel_hi:[1,1,1]
	v_pk_mul_f32 v[44:45], v[104:105], v[86:87] op_sel_hi:[1,0]
	v_pk_fma_f32 v[12:13], v[12:13], v[98:99], v[44:45] op_sel:[0,1,0] op_sel_hi:[1,1,1]
	v_pk_fma_f32 v[38:39], v[12:13], v[86:87], v[38:39] op_sel:[0,1,0] op_sel_hi:[1,1,1]
	v_pk_mul_f32 v[42:43], v[104:105], v[88:89] op_sel_hi:[1,0]
	v_pk_fma_f32 v[14:15], v[14:15], v[100:101], v[42:43] op_sel:[0,0,0] op_sel_hi:[1,0,1]
	v_pk_fma_f32 v[38:39], v[14:15], v[88:89], v[38:39] op_sel:[0,1,0] op_sel_hi:[1,1,1]
	v_pk_mul_f32 v[44:45], v[104:105], v[90:91] op_sel_hi:[1,0]
	v_pk_fma_f32 v[16:17], v[16:17], v[100:101], v[44:45] op_sel:[0,1,0] op_sel_hi:[1,1,1]
	v_pk_fma_f32 v[38:39], v[16:17], v[90:91], v[38:39] op_sel:[0,1,0] op_sel_hi:[1,1,1]
	v_pk_mul_f32 v[42:43], v[104:105], v[92:93] op_sel_hi:[1,0]
	v_pk_fma_f32 v[18:19], v[18:19], v[102:103], v[42:43] op_sel:[0,0,0] op_sel_hi:[1,0,1]
	v_pk_fma_f32 v[38:39], v[18:19], v[92:93], v[38:39] op_sel:[0,1,0] op_sel_hi:[1,1,1]
	v_pk_mul_f32 v[44:45], v[104:105], v[94:95] op_sel_hi:[1,0]
	v_pk_fma_f32 v[20:21], v[20:21], v[102:103], v[44:45] op_sel:[0,1,0] op_sel_hi:[1,1,1]
	v_pk_fma_f32 v[38:39], v[20:21], v[94:95], v[38:39] op_sel:[0,1,0] op_sel_hi:[1,1,1]
	s_add_u32 s14, s14, 0x1000
	s_addc_u32 s15, s15, 0
	v_add_f32_dpp v38, v38, v38 quad_perm:[1,0,3,2] row_mask:0xf bank_mask:0xf bound_ctrl:1
	v_add_f32_dpp v39, v39, v39 quad_perm:[1,0,3,2] row_mask:0xf bank_mask:0xf bound_ctrl:1
	s_nop 0
	v_add_f32_dpp v38, v38, v38 quad_perm:[2,3,0,1] row_mask:0xf bank_mask:0xf bound_ctrl:1
	v_add_f32_dpp v39, v39, v39 quad_perm:[2,3,0,1] row_mask:0xf bank_mask:0xf bound_ctrl:1
	s_nop 0
	v_add_f32_dpp v38, v38, v38 row_half_mirror row_mask:0xf bank_mask:0xf bound_ctrl:1
	v_add_f32_dpp v39, v39, v39 row_half_mirror row_mask:0xf bank_mask:0xf bound_ctrl:1
	s_nop 0
	v_add_f32_dpp v38, v38, v38 row_mirror row_mask:0xf bank_mask:0xf bound_ctrl:1
	v_add_f32_dpp v39, v39, v39 row_mirror row_mask:0xf bank_mask:0xf bound_ctrl:1
	v_pk_mul_f32 v[38:39], v[38:39], v[40:41] op_sel_hi:[1,0]
	v_cvt_pk_bf16_f32 v47, v38, v39
	s_mov_b64 exec, s[2:3]
	global_store_dword v46, v47, s[14:15] offset:-4096
	s_mov_b64 exec, -1
	s_waitcnt vmcnt(8)
	v_lshlrev_b32_e32 v144, 16, v110
	v_lshlrev_b32_e32 v145, 16, v111
	v_and_b32_e32 v146, s17, v110
	v_and_b32_e32 v147, s17, v111
	v_lshlrev_b32_e32 v148, 16, v112
	v_lshlrev_b32_e32 v149, 16, v113
	v_and_b32_e32 v150, s17, v112
	v_and_b32_e32 v151, s17, v113
	v_lshlrev_b32_e32 v152, 16, v114
	v_and_b32_e32 v153, s17, v114
	ds_write_b128 v26, v[144:147] offset:0
	ds_write_b128 v26, v[148:151] offset:8192
	ds_write_b64 v27, v[116:117]
	ds_write_b64 v28, v[152:153]
	s_mov_b32 s0, s20
	s_mov_b32 s20, s21
	s_mov_b32 s21, s22
	s_mov_b32 s22, s0
	v_mov_b32_e32 v22, v24
	v_mov_b32_e32 v23, v25
	v_add_u32_e32 v24, s21, v2
	v_add_u32_e32 v25, s21, v3
	v_add_u32_e32 v26, s22, v29
	v_add_u32_e32 v27, s22, v30
	v_add_u32_e32 v28, s22, v31
	s_waitcnt lgkmcnt(0)
	s_barrier
	s_add_i32 s16, s16, 8
	s_cmpk_lt_u32 s16, 0x800
	s_cbranch_scc1 .Lgla2_loop
	v_readlane_b32 s0, v255, 18
	v_readlane_b32 s1, v255, 19
	s_load_dwordx2 s[2:3], s[0:1], 0xe8
	s_lshr_b32 s0, s18, 5
	s_lshl_b32 s4, s0, 17
	s_add_u32 s4, s4, 74236160
	v_lshl_add_u32 v42, v46, 1, v4
	s_waitcnt lgkmcnt(0)
	s_add_u32 s2, s2, s4
	s_addc_u32 s3, s3, 0
	global_store_dwordx2 v42, v[6:7], s[2:3] offset:0
	global_store_dwordx2 v42, v[8:9], s[2:3] offset:1024
	global_store_dwordx2 v42, v[10:11], s[2:3] offset:2048
	global_store_dwordx2 v42, v[12:13], s[2:3] offset:3072
	s_add_u32 s2, s2, 0x1000
	s_addc_u32 s3, s3, 0
	global_store_dwordx2 v42, v[14:15], s[2:3] offset:0
	global_store_dwordx2 v42, v[16:17], s[2:3] offset:1024
	global_store_dwordx2 v42, v[18:19], s[2:3] offset:2048
	global_store_dwordx2 v42, v[20:21], s[2:3] offset:3072
	s_add_i32 s18, s18, s19
	s_waitcnt vmcnt(0)
	s_cmpk_lt_i32 s18, 0x400
	s_cbranch_scc1 .Lgla2_item
	s_branch .LBB0_80
